# V^T loop: de-serialised loads + XOR-swizzled LDS transpose tile (removes 12-way ds_write_b16 bank conflicts); A-attn first-batch wait moved to first consumer
# baseline (speedup 1.0000x reference)
.LBB0_377:
	v_readlane_b32 s0, v254, 50
	v_readlane_b32 s1, v254, 51
	s_and_b64 s[0:1], s[0:1], exec
	s_cselect_b32 s65, 11, 13
	s_cmpk_gt_i32 s22, 0xbff
	v_readlane_b32 s20, v253, 28
	s_movk_i32 s21, 0xc00
	s_cbranch_scc1 .LBB0_380
	s_mov_b32 s4, 0x15555556
	s_add_u32 s0, s16, 0x5e00000
	s_mul_i32 s3, s24, 0x3600
	v_mul_hi_u32 v1, v33, s4
	s_addc_u32 s1, s17, 0
	s_add_i32 s3, s3, 0
	v_mul_u32_u24_e32 v3, 12, v1
	s_waitcnt lgkmcnt(0)
	v_mov_b32_e32 v9, s3
	v_sub_u32_e32 v3, v33, v3
	v_and_b32_e32 v6, 3, v1
	s_movk_i32 s5, 0x480
	v_lshlrev_b32_e32 v8, 2, v1
	v_or_b32_e32 v15, 64, v33
	v_lshlrev_b32_e32 v4, 3, v3
	v_mad_i32_i24 v3, v3, s5, v9
	v_lshlrev_b32_e32 v6, 1, v6
	v_and_b32_e32 v8, 16, v8
	s_waitcnt vmcnt(0)
	v_mul_hi_u32 v56, v15, s4
	v_add3_u32 v3, v3, v6, v8
	v_mul_u32_u24_e32 v6, 12, v56
	v_sub_u32_e32 v8, v15, v6
	v_and_b32_e32 v10, 3, v56
	v_lshlrev_b32_e32 v6, 3, v8
	v_mul_i32_i24_e32 v8, 0x480, v8
	v_lshlrev_b32_e32 v10, 1, v10
	v_add3_u32 v8, s3, v8, v10
	v_lshlrev_b32_e32 v10, 2, v56
	v_or_b32_e32 v17, 0x80, v33
	v_and_b32_e32 v10, 16, v10
	v_and_b32_e32 v12, 8, v56
	v_mul_hi_u32 v58, v17, s4
	v_add3_u32 v57, v8, v10, v12
	v_mul_u32_u24_e32 v8, 12, v58
	v_sub_u32_e32 v10, v17, v8
	v_and_b32_e32 v12, 3, v58
	v_lshlrev_b32_e32 v14, 2, v58
	v_or_b32_e32 v19, 0xc0, v33
	v_lshlrev_b32_e32 v8, 3, v10
	v_mad_i32_i24 v10, v10, s5, v9
	v_lshlrev_b32_e32 v12, 1, v12
	v_and_b32_e32 v14, 16, v14
	v_mul_hi_u32 v60, v19, s4
	v_add3_u32 v59, v10, v12, v14
	v_mul_u32_u24_e32 v10, 12, v60
	v_sub_u32_e32 v12, v19, v10
	v_and_b32_e32 v14, 19, v60
	v_lshlrev_b32_e32 v16, 2, v60
	v_or_b32_e32 v21, 0x100, v33
	v_lshlrev_b32_e32 v10, 3, v12
	v_mad_i32_i24 v12, v12, s5, v9
	v_lshlrev_b32_e32 v14, 1, v14
	v_and_b32_e32 v16, 16, v16
	v_mul_hi_u32 v62, v21, s4
	v_add3_u32 v61, v12, v14, v16
	v_mul_u32_u24_e32 v12, 12, v62
	v_sub_u32_e32 v14, v21, v12
	v_and_b32_e32 v16, 19, v62
	v_lshlrev_b32_e32 v12, 3, v14
	v_mul_i32_i24_e32 v14, 0x480, v14
	v_lshlrev_b32_e32 v16, 1, v16
	v_add3_u32 v14, s3, v14, v16
	v_lshlrev_b32_e32 v16, 2, v62
	v_or_b32_e32 v23, 0x140, v33
	v_and_b32_e32 v16, 16, v16
	v_and_b32_e32 v18, 8, v62
	v_mul_hi_u32 v64, v23, s4
	v_add3_u32 v63, v14, v16, v18
	v_mul_u32_u24_e32 v14, 12, v64
	v_sub_u32_e32 v16, v23, v14
	v_and_b32_e32 v18, 19, v64
	v_lshlrev_b32_e32 v20, 2, v64
	v_or_b32_e32 v25, 0x180, v33
	v_lshlrev_b32_e32 v14, 3, v16
	v_mad_i32_i24 v16, v16, s5, v9
	v_lshlrev_b32_e32 v18, 1, v18
	v_and_b32_e32 v20, 16, v20
	v_mul_hi_u32 v66, v25, s4
	v_add3_u32 v65, v16, v18, v20
	v_mul_u32_u24_e32 v16, 12, v66
	v_sub_u32_e32 v18, v25, v16
	v_and_b32_e32 v20, 51, v66
	v_lshlrev_b32_e32 v22, 2, v66
	v_or_b32_e32 v27, 0x1c0, v33
	v_lshlrev_b32_e32 v16, 3, v18
	v_mad_i32_i24 v18, v18, s5, v9
	v_lshlrev_b32_e32 v20, 1, v20
	v_and_b32_e32 v22, 16, v22
	v_mul_hi_u32 v68, v27, s4
	v_add3_u32 v67, v18, v20, v22
	v_mul_u32_u24_e32 v18, 12, v68
	v_sub_u32_e32 v20, v27, v18
	v_and_b32_e32 v22, 51, v68
	v_lshlrev_b32_e32 v18, 3, v20
	v_mul_i32_i24_e32 v20, 0x480, v20
	v_lshlrev_b32_e32 v22, 1, v22
	v_add3_u32 v20, s3, v20, v22
	v_lshlrev_b32_e32 v22, 2, v68
	v_or_b32_e32 v29, 0x200, v33
	v_and_b32_e32 v22, 16, v22
	v_and_b32_e32 v24, 8, v68
	v_mul_hi_u32 v70, v29, s4
	v_add3_u32 v69, v20, v22, v24
	v_mul_u32_u24_e32 v20, 12, v70
	v_sub_u32_e32 v22, v29, v20
	v_and_b32_e32 v24, 51, v70
	v_lshlrev_b32_e32 v26, 2, v70
	v_or_b32_e32 v31, 0x240, v33
	v_lshlrev_b32_e32 v20, 3, v22
	v_mad_i32_i24 v22, v22, s5, v9
	v_lshlrev_b32_e32 v24, 1, v24
	v_and_b32_e32 v26, 16, v26
	v_mul_hi_u32 v72, v31, s4
	v_add3_u32 v71, v22, v24, v26
	v_mul_u32_u24_e32 v22, 12, v72
	v_sub_u32_e32 v24, v31, v22
	v_and_b32_e32 v26, 51, v72
	v_lshlrev_b32_e32 v28, 2, v72
	v_or_b32_e32 v35, 0x280, v33
	v_lshlrev_b32_e32 v22, 3, v24
	v_mad_i32_i24 v24, v24, s5, v9
	v_lshlrev_b32_e32 v26, 1, v26
	v_and_b32_e32 v28, 16, v28
	v_mul_hi_u32 v74, v35, s4
	v_add3_u32 v73, v24, v26, v28
	v_mul_u32_u24_e32 v24, 12, v74
	v_sub_u32_e32 v26, v35, v24
	v_and_b32_e32 v28, 51, v74
	v_lshlrev_b32_e32 v24, 3, v26
	v_mul_i32_i24_e32 v26, 0x480, v26
	v_lshlrev_b32_e32 v28, 1, v28
	v_add3_u32 v26, s3, v26, v28
	v_lshlrev_b32_e32 v28, 2, v74
	v_or_b32_e32 v33, 0x2c0, v33
	v_and_b32_e32 v28, 16, v28
	v_and_b32_e32 v30, 8, v74
	v_mul_hi_u32 v76, v33, s4
	v_add3_u32 v75, v26, v28, v30
	v_mul_u32_u24_e32 v26, 12, v76
	v_sub_u32_e32 v28, v33, v26
	v_and_b32_e32 v30, 51, v76
	v_lshlrev_b32_e32 v5, 5, v81
	v_lshlrev_b32_e32 v26, 3, v28
	v_mad_i32_i24 v9, v28, s5, v9
	v_lshlrev_b32_e32 v28, 1, v30
	v_lshlrev_b32_e32 v30, 2, v76
	v_and_b32_e32 v7, 32, v5
	v_and_b32_e32 v30, 16, v30
	v_add3_u32 v77, v9, v28, v30
	v_or_b32_e32 v9, v80, v7
	v_lshlrev_b32_e32 v28, 3, v9
	v_lshrrev_b32_e32 v9, 3, v15
	v_mul_u32_u24_e32 v15, 0x90, v9
	v_or_b32_e32 v9, v9, v7
	v_lshlrev_b32_e32 v30, 3, v9
	v_lshrrev_b32_e32 v9, 3, v17
	v_mul_u32_u24_e32 v17, 0x90, v9
	v_or_b32_e32 v9, v9, v7
	v_lshlrev_b32_e32 v32, 3, v9
	v_lshrrev_b32_e32 v9, 3, v19
	v_mul_u32_u24_e32 v19, 0x90, v9
	v_or_b32_e32 v9, v9, v7
	v_lshlrev_b32_e32 v34, 3, v9
	v_lshrrev_b32_e32 v9, 3, v21
	v_mul_u32_u24_e32 v21, 0x90, v9
	v_and_or_b32 v9, v9, 7, v7
	v_lshlrev_b32_e32 v36, 3, v9
	v_lshrrev_b32_e32 v9, 3, v23
	v_mul_u32_u24_e32 v23, 0x90, v9
	v_and_or_b32 v9, v9, 15, v7
	v_lshlrev_b32_e32 v38, 3, v9
	v_lshrrev_b32_e32 v9, 3, v25
	v_mul_u32_u24_e32 v25, 0x90, v9
	v_and_or_b32 v9, v9, 23, v7
	v_lshlrev_b32_e32 v40, 3, v9
	v_lshrrev_b32_e32 v9, 3, v27
	v_and_or_b32 v7, v9, 31, v7
	v_lshlrev_b32_e32 v42, 3, v7
	v_lshrrev_b32_e32 v7, 3, v29
	v_mul_u32_u24_e32 v27, 0x90, v9
	v_mul_u32_u24_e32 v9, 0x90, v7
	v_bitop3_b32 v7, v7, 39, v5 bitop3:0xc8
	v_lshlrev_b32_e32 v44, 3, v7
	v_lshrrev_b32_e32 v7, 3, v31
	v_mul_u32_u24_e32 v29, 0x90, v7
	v_bitop3_b32 v7, v7, 47, v5 bitop3:0xc8
	v_lshlrev_b32_e32 v46, 3, v7
	v_lshrrev_b32_e32 v7, 3, v35
	v_mul_u32_u24_e32 v31, 0x90, v7
	v_bitop3_b32 v7, v7, 55, v5 bitop3:0xc8
	v_lshlrev_b32_e32 v48, 3, v7
	v_lshrrev_b32_e32 v7, 3, v33
	v_bitop3_b32 v5, v7, 63, v5 bitop3:0xc8
	v_lshl_add_u32 v11, v82, 4, s3
	v_mul_u32_u24_e32 v13, 0x90, v80
	v_mul_u32_u24_e32 v33, 0x90, v7
	v_lshlrev_b32_e32 v50, 3, v5
	s_lshl_b32 s3, s24, 6
	v_readlane_b32 s4, v253, 27
	v_lshrrev_b32_e32 v0, 2, v82
	v_bfe_u32 v2, v81, 1, 1
	s_add_i32 s8, s4, s3
	v_lshlrev_b32_e32 v4, 1, v4
	v_lshlrev_b32_e32 v6, 1, v6
	v_lshlrev_b32_e32 v8, 1, v8
	v_lshlrev_b32_e32 v10, 1, v10
	v_lshlrev_b32_e32 v12, 1, v12
	v_lshlrev_b32_e32 v14, 1, v14
	v_lshlrev_b32_e32 v16, 1, v16
	v_lshlrev_b32_e32 v18, 1, v18
	v_lshlrev_b32_e32 v20, 1, v20
	v_lshlrev_b32_e32 v22, 1, v22
	v_lshlrev_b32_e32 v24, 1, v24
	v_lshlrev_b32_e32 v26, 1, v26
	v_add_u32_e32 v78, v11, v13
	v_lshlrev_b32_e32 v28, 1, v28
	v_add_u32_e32 v79, v11, v15
	v_lshlrev_b32_e32 v30, 1, v30
	v_add_u32_e32 v80, v11, v17
	v_lshlrev_b32_e32 v32, 1, v32
	v_add_u32_e32 v81, v11, v19
	v_lshlrev_b32_e32 v34, 1, v34
	v_add_u32_e32 v82, v11, v21
	v_lshlrev_b32_e32 v36, 1, v36
	v_add_u32_e32 v83, v11, v23
	v_lshlrev_b32_e32 v38, 1, v38
	v_add_u32_e32 v84, v11, v25
	v_lshlrev_b32_e32 v40, 1, v40
	v_add_u32_e32 v85, v11, v27
	v_lshlrev_b32_e32 v42, 1, v42
	v_add_u32_e32 v86, v11, v9
	v_lshlrev_b32_e32 v44, 1, v44
	v_add_u32_e32 v87, v11, v29
	v_lshlrev_b32_e32 v46, 1, v46
	v_add_u32_e32 v88, v11, v31
	v_lshlrev_b32_e32 v48, 1, v48
	v_add_u32_e32 v89, v11, v33
	v_lshlrev_b32_e32 v50, 1, v50
	v_lshrrev_b32_e32 v146, 6, v220
	v_mul_u32_u24_e32 v146, 12, v146
	v_and_b32_e32 v147, 7, v220
	v_lshlrev_b32_e32 v147, 4, v147
	v_lshrrev_b32_e32 v148, 7, v3
	v_mul_u32_u24_e32 v148, 0x1c72, v148
	v_lshrrev_b32_e32 v148, 16, v148
	v_sub_u32_e32 v148, v148, v146
	v_and_b32_e32 v148, 7, v148
	v_lshlrev_b32_e32 v148, 4, v148
	v_xor_b32_e32 v3, v3, v148
	v_lshrrev_b32_e32 v148, 7, v57
	v_mul_u32_u24_e32 v148, 0x1c72, v148
	v_lshrrev_b32_e32 v148, 16, v148
	v_sub_u32_e32 v148, v148, v146
	v_and_b32_e32 v148, 7, v148
	v_lshlrev_b32_e32 v148, 4, v148
	v_xor_b32_e32 v57, v57, v148
	v_add_u32_e32 v59, 8, v59
	v_lshrrev_b32_e32 v148, 7, v59
	v_mul_u32_u24_e32 v148, 0x1c72, v148
	v_lshrrev_b32_e32 v148, 16, v148
	v_sub_u32_e32 v148, v148, v146
	v_and_b32_e32 v148, 7, v148
	v_lshlrev_b32_e32 v148, 4, v148
	v_xor_b32_e32 v59, v59, v148
	v_lshrrev_b32_e32 v148, 7, v61
	v_mul_u32_u24_e32 v148, 0x1c72, v148
	v_lshrrev_b32_e32 v148, 16, v148
	v_sub_u32_e32 v148, v148, v146
	v_and_b32_e32 v148, 7, v148
	v_lshlrev_b32_e32 v148, 4, v148
	v_xor_b32_e32 v61, v61, v148
	v_lshrrev_b32_e32 v148, 7, v63
	v_mul_u32_u24_e32 v148, 0x1c72, v148
	v_lshrrev_b32_e32 v148, 16, v148
	v_sub_u32_e32 v148, v148, v146
	v_and_b32_e32 v148, 7, v148
	v_lshlrev_b32_e32 v148, 4, v148
	v_xor_b32_e32 v63, v63, v148
	v_add_u32_e32 v65, 8, v65
	v_lshrrev_b32_e32 v148, 7, v65
	v_mul_u32_u24_e32 v148, 0x1c72, v148
	v_lshrrev_b32_e32 v148, 16, v148
	v_sub_u32_e32 v148, v148, v146
	v_and_b32_e32 v148, 7, v148
	v_lshlrev_b32_e32 v148, 4, v148
	v_xor_b32_e32 v65, v65, v148
	v_lshrrev_b32_e32 v148, 7, v67
	v_mul_u32_u24_e32 v148, 0x1c72, v148
	v_lshrrev_b32_e32 v148, 16, v148
	v_sub_u32_e32 v148, v148, v146
	v_and_b32_e32 v148, 7, v148
	v_lshlrev_b32_e32 v148, 4, v148
	v_xor_b32_e32 v67, v67, v148
	v_lshrrev_b32_e32 v148, 7, v69
	v_mul_u32_u24_e32 v148, 0x1c72, v148
	v_lshrrev_b32_e32 v148, 16, v148
	v_sub_u32_e32 v148, v148, v146
	v_and_b32_e32 v148, 7, v148
	v_lshlrev_b32_e32 v148, 4, v148
	v_xor_b32_e32 v69, v69, v148
	v_add_u32_e32 v71, 8, v71
	v_lshrrev_b32_e32 v148, 7, v71
	v_mul_u32_u24_e32 v148, 0x1c72, v148
	v_lshrrev_b32_e32 v148, 16, v148
	v_sub_u32_e32 v148, v148, v146
	v_and_b32_e32 v148, 7, v148
	v_lshlrev_b32_e32 v148, 4, v148
	v_xor_b32_e32 v71, v71, v148
	v_lshrrev_b32_e32 v148, 7, v73
	v_mul_u32_u24_e32 v148, 0x1c72, v148
	v_lshrrev_b32_e32 v148, 16, v148
	v_sub_u32_e32 v148, v148, v146
	v_and_b32_e32 v148, 7, v148
	v_lshlrev_b32_e32 v148, 4, v148
	v_xor_b32_e32 v73, v73, v148
	v_lshrrev_b32_e32 v148, 7, v75
	v_mul_u32_u24_e32 v148, 0x1c72, v148
	v_lshrrev_b32_e32 v148, 16, v148
	v_sub_u32_e32 v148, v148, v146
	v_and_b32_e32 v148, 7, v148
	v_lshlrev_b32_e32 v148, 4, v148
	v_xor_b32_e32 v75, v75, v148
	v_add_u32_e32 v77, 8, v77
	v_lshrrev_b32_e32 v148, 7, v77
	v_mul_u32_u24_e32 v148, 0x1c72, v148
	v_lshrrev_b32_e32 v148, 16, v148
	v_sub_u32_e32 v148, v148, v146
	v_and_b32_e32 v148, 7, v148
	v_lshlrev_b32_e32 v148, 4, v148
	v_xor_b32_e32 v77, v77, v148
	v_lshrrev_b32_e32 v148, 7, v78
	v_mul_u32_u24_e32 v148, 0x1c72, v148
	v_lshrrev_b32_e32 v148, 16, v148
	v_sub_u32_e32 v148, v148, v146
	v_and_b32_e32 v148, 7, v148
	v_lshlrev_b32_e32 v148, 4, v148
	v_xor_b32_e32 v149, v147, v148
	v_sub_u32_e32 v149, v149, v147
	v_add_u32_e32 v78, v78, v149
	v_lshrrev_b32_e32 v148, 7, v79
	v_mul_u32_u24_e32 v148, 0x1c72, v148
	v_lshrrev_b32_e32 v148, 16, v148
	v_sub_u32_e32 v148, v148, v146
	v_and_b32_e32 v148, 7, v148
	v_lshlrev_b32_e32 v148, 4, v148
	v_xor_b32_e32 v149, v147, v148
	v_sub_u32_e32 v149, v149, v147
	v_add_u32_e32 v79, v79, v149
	v_lshrrev_b32_e32 v148, 7, v80
	v_mul_u32_u24_e32 v148, 0x1c72, v148
	v_lshrrev_b32_e32 v148, 16, v148
	v_sub_u32_e32 v148, v148, v146
	v_and_b32_e32 v148, 7, v148
	v_lshlrev_b32_e32 v148, 4, v148
	v_xor_b32_e32 v149, v147, v148
	v_sub_u32_e32 v149, v149, v147
	v_add_u32_e32 v80, v80, v149
	v_lshrrev_b32_e32 v148, 7, v81
	v_mul_u32_u24_e32 v148, 0x1c72, v148
	v_lshrrev_b32_e32 v148, 16, v148
	v_sub_u32_e32 v148, v148, v146
	v_and_b32_e32 v148, 7, v148
	v_lshlrev_b32_e32 v148, 4, v148
	v_xor_b32_e32 v149, v147, v148
	v_sub_u32_e32 v149, v149, v147
	v_add_u32_e32 v81, v81, v149
	v_lshrrev_b32_e32 v148, 7, v82
	v_mul_u32_u24_e32 v148, 0x1c72, v148
	v_lshrrev_b32_e32 v148, 16, v148
	v_sub_u32_e32 v148, v148, v146
	v_and_b32_e32 v148, 7, v148
	v_lshlrev_b32_e32 v148, 4, v148
	v_xor_b32_e32 v149, v147, v148
	v_sub_u32_e32 v149, v149, v147
	v_add_u32_e32 v82, v82, v149
	v_lshrrev_b32_e32 v148, 7, v83
	v_mul_u32_u24_e32 v148, 0x1c72, v148
	v_lshrrev_b32_e32 v148, 16, v148
	v_sub_u32_e32 v148, v148, v146
	v_and_b32_e32 v148, 7, v148
	v_lshlrev_b32_e32 v148, 4, v148
	v_xor_b32_e32 v149, v147, v148
	v_sub_u32_e32 v149, v149, v147
	v_add_u32_e32 v83, v83, v149
	v_lshrrev_b32_e32 v148, 7, v84
	v_mul_u32_u24_e32 v148, 0x1c72, v148
	v_lshrrev_b32_e32 v148, 16, v148
	v_sub_u32_e32 v148, v148, v146
	v_and_b32_e32 v148, 7, v148
	v_lshlrev_b32_e32 v148, 4, v148
	v_xor_b32_e32 v149, v147, v148
	v_sub_u32_e32 v149, v149, v147
	v_add_u32_e32 v84, v84, v149
	v_lshrrev_b32_e32 v148, 7, v85
	v_mul_u32_u24_e32 v148, 0x1c72, v148
	v_lshrrev_b32_e32 v148, 16, v148
	v_sub_u32_e32 v148, v148, v146
	v_and_b32_e32 v148, 7, v148
	v_lshlrev_b32_e32 v148, 4, v148
	v_xor_b32_e32 v149, v147, v148
	v_sub_u32_e32 v149, v149, v147
	v_add_u32_e32 v85, v85, v149
	v_lshrrev_b32_e32 v148, 7, v86
	v_mul_u32_u24_e32 v148, 0x1c72, v148
	v_lshrrev_b32_e32 v148, 16, v148
	v_sub_u32_e32 v148, v148, v146
	v_and_b32_e32 v148, 7, v148
	v_lshlrev_b32_e32 v148, 4, v148
	v_xor_b32_e32 v149, v147, v148
	v_sub_u32_e32 v149, v149, v147
	v_add_u32_e32 v86, v86, v149
	v_lshrrev_b32_e32 v148, 7, v87
	v_mul_u32_u24_e32 v148, 0x1c72, v148
	v_lshrrev_b32_e32 v148, 16, v148
	v_sub_u32_e32 v148, v148, v146
	v_and_b32_e32 v148, 7, v148
	v_lshlrev_b32_e32 v148, 4, v148
	v_xor_b32_e32 v149, v147, v148
	v_sub_u32_e32 v149, v149, v147
	v_add_u32_e32 v87, v87, v149
	v_lshrrev_b32_e32 v148, 7, v88
	v_mul_u32_u24_e32 v148, 0x1c72, v148
	v_lshrrev_b32_e32 v148, 16, v148
	v_sub_u32_e32 v148, v148, v146
	v_and_b32_e32 v148, 7, v148
	v_lshlrev_b32_e32 v148, 4, v148
	v_xor_b32_e32 v149, v147, v148
	v_sub_u32_e32 v149, v149, v147
	v_add_u32_e32 v88, v88, v149
	v_lshrrev_b32_e32 v148, 7, v89
	v_mul_u32_u24_e32 v148, 0x1c72, v148
	v_lshrrev_b32_e32 v148, 16, v148
	v_sub_u32_e32 v148, v148, v146
	v_and_b32_e32 v148, 7, v148
	v_lshlrev_b32_e32 v148, 4, v148
	v_xor_b32_e32 v149, v147, v148
	v_sub_u32_e32 v149, v149, v147
	v_add_u32_e32 v89, v89, v149
.LBB0_379:
	s_and_b32 s3, s8, 0x3fc0
	s_lshr_b32 s9, s3, s65
	s_and_b32 s5, s3, s23
	s_ashr_i32 s3, s22, 9
	s_and_b32 s10, s3, -2
	s_sub_i32 s11, s65, s10
	s_lshl_b32 s16, -1, s11
	v_or_b32_e32 v5, s5, v1
	v_mov_b32_e32 v27, s5
	v_lshrrev_b32_e32 v5, s11, v5
	v_bitop3_b32 v52, v1, s16, v27 bitop3:0x32
	s_lshl_b32 s9, s9, s65
	v_mov_b32_e32 v53, v205
	v_add_u32_e32 v204, s9, v5
	v_lshlrev_b64 v[52:53], s10, v[52:53]
	v_lshl_add_u64 v[54:55], v[204:205], 0, v[52:53]
	v_mov_b64_e32 v[52:53], s[14:15]
	s_ashr_i32 s4, s22, 8
	v_mad_u64_u32 v[90:91], s[18:19], v54, s81, v[52:53]
	s_mul_i32 s6, s4, 0x60
	v_mov_b32_e32 v54, v91
	s_ashr_i32 s7, s6, 31
	v_mad_u64_u32 v[54:55], s[18:19], v55, s81, v[54:55]
	v_mov_b32_e32 v91, v54
	s_lshl_b64 s[6:7], s[6:7], 1
	v_lshl_add_u64 v[54:55], v[90:91], 0, s[6:7]
	v_mov_b32_e32 v5, v205
	v_lshl_add_u64 v[54:55], v[54:55], 0, v[4:5]
	v_add_co_u32_e32 v54, vcc, s92, v54
	v_or_b32_e32 v5, s5, v56
	s_nop 0
	v_addc_co_u32_e32 v55, vcc, 0, v55, vcc
	global_load_dwordx4 v[96:99], v[54:55], off offset:512
	v_lshrrev_b32_e32 v5, s11, v5
	v_bitop3_b32 v54, v56, s16, v27 bitop3:0x32
	v_mov_b32_e32 v55, v205
	v_add_u32_e32 v204, s9, v5
	v_lshlrev_b64 v[54:55], s10, v[54:55]
	v_lshl_add_u64 v[54:55], v[204:205], 0, v[54:55]
	v_mov_b32_e32 v7, v205
	v_or_b32_e32 v5, s5, v58
	v_lshrrev_b32_e32 v5, s11, v5
	v_add_u32_e32 v204, s9, v5
	v_mov_b32_e32 v9, v205
	v_or_b32_e32 v5, s5, v60
	v_lshrrev_b32_e32 v5, s11, v5
	v_mov_b32_e32 v11, v205
	v_mov_b32_e32 v13, v205
	v_mov_b32_e32 v15, v205
	v_mov_b32_e32 v17, v205
	v_mov_b32_e32 v19, v205
	v_mov_b32_e32 v21, v205
	v_mov_b32_e32 v23, v205
	v_mov_b32_e32 v25, v205
	v_mov_b32_e32 v29, v205
	v_mov_b32_e32 v31, v205
	v_mov_b32_e32 v33, v205
	v_mov_b32_e32 v35, v205
	v_mov_b32_e32 v37, v205
	v_mov_b32_e32 v39, v205
	v_mov_b32_e32 v41, v205
	v_mov_b32_e32 v43, v205
	v_mov_b32_e32 v45, v205
	v_mov_b32_e32 v47, v205
	v_mov_b32_e32 v49, v205
	v_mov_b32_e32 v51, v205
	s_add_i32 s22, s22, s72
	s_add_i32 s8, s8, s20
	v_mad_u64_u32 v[90:91], s[18:19], v54, s81, v[52:53]
	v_mov_b32_e32 v54, v91
	v_mad_u64_u32 v[54:55], s[18:19], v55, s81, v[54:55]
	v_mov_b32_e32 v91, v54
	v_lshl_add_u64 v[54:55], v[90:91], 0, s[6:7]
	v_lshl_add_u64 v[54:55], v[54:55], 0, v[6:7]
	v_add_co_u32_e32 v54, vcc, s92, v54
	s_nop 1
	v_addc_co_u32_e32 v55, vcc, 0, v55, vcc
	global_load_dwordx4 v[100:103], v[54:55], off offset:512
	v_bitop3_b32 v54, v58, s16, v27 bitop3:0x32
	v_mov_b32_e32 v55, v205
	v_lshlrev_b64 v[54:55], s10, v[54:55]
	v_lshl_add_u64 v[54:55], v[204:205], 0, v[54:55]
	v_add_u32_e32 v204, s9, v5
	v_or_b32_e32 v5, s5, v62
	v_lshrrev_b32_e32 v5, s11, v5
	v_mad_u64_u32 v[90:91], s[18:19], v54, s81, v[52:53]
	v_mov_b32_e32 v54, v91
	v_mad_u64_u32 v[54:55], s[18:19], v55, s81, v[54:55]
	v_mov_b32_e32 v91, v54
	v_lshl_add_u64 v[54:55], v[90:91], 0, s[6:7]
	v_lshl_add_u64 v[54:55], v[54:55], 0, v[8:9]
	v_add_co_u32_e32 v54, vcc, s92, v54
	s_nop 1
	v_addc_co_u32_e32 v55, vcc, 0, v55, vcc
	global_load_dwordx4 v[104:107], v[54:55], off offset:512
	v_bitop3_b32 v54, v60, s16, v27 bitop3:0x32
	v_mov_b32_e32 v55, v205
	v_lshlrev_b64 v[54:55], s10, v[54:55]
	v_lshl_add_u64 v[54:55], v[204:205], 0, v[54:55]
	v_add_u32_e32 v204, s9, v5
	v_or_b32_e32 v5, s5, v64
	v_lshrrev_b32_e32 v5, s11, v5
	v_mad_u64_u32 v[90:91], s[18:19], v54, s81, v[52:53]
	v_mov_b32_e32 v54, v91
	v_mad_u64_u32 v[54:55], s[18:19], v55, s81, v[54:55]
	v_mov_b32_e32 v91, v54
	v_lshl_add_u64 v[54:55], v[90:91], 0, s[6:7]
	v_lshl_add_u64 v[54:55], v[54:55], 0, v[10:11]
	v_add_co_u32_e32 v54, vcc, s92, v54
	s_nop 1
	v_addc_co_u32_e32 v55, vcc, 0, v55, vcc
	global_load_dwordx4 v[108:111], v[54:55], off offset:512
	v_bitop3_b32 v54, v62, s16, v27 bitop3:0x32
	v_mov_b32_e32 v55, v205
	v_lshlrev_b64 v[54:55], s10, v[54:55]
	v_lshl_add_u64 v[54:55], v[204:205], 0, v[54:55]
	v_add_u32_e32 v204, s9, v5
	v_or_b32_e32 v5, s5, v66
	v_lshrrev_b32_e32 v5, s11, v5
	v_mad_u64_u32 v[90:91], s[18:19], v54, s81, v[52:53]
	v_mov_b32_e32 v54, v91
	v_mad_u64_u32 v[54:55], s[18:19], v55, s81, v[54:55]
	v_mov_b32_e32 v91, v54
	v_lshl_add_u64 v[54:55], v[90:91], 0, s[6:7]
	v_lshl_add_u64 v[54:55], v[54:55], 0, v[12:13]
	v_add_co_u32_e32 v54, vcc, s92, v54
	s_nop 1
	v_addc_co_u32_e32 v55, vcc, 0, v55, vcc
	global_load_dwordx4 v[112:115], v[54:55], off offset:512
	v_bitop3_b32 v54, v64, s16, v27 bitop3:0x32
	v_mov_b32_e32 v55, v205
	v_lshlrev_b64 v[54:55], s10, v[54:55]
	v_lshl_add_u64 v[54:55], v[204:205], 0, v[54:55]
	v_add_u32_e32 v204, s9, v5
	v_or_b32_e32 v5, s5, v68
	v_lshrrev_b32_e32 v5, s11, v5
	v_mad_u64_u32 v[90:91], s[18:19], v54, s81, v[52:53]
	v_mov_b32_e32 v54, v91
	v_mad_u64_u32 v[54:55], s[18:19], v55, s81, v[54:55]
	v_mov_b32_e32 v91, v54
	v_lshl_add_u64 v[54:55], v[90:91], 0, s[6:7]
	v_lshl_add_u64 v[54:55], v[54:55], 0, v[14:15]
	v_add_co_u32_e32 v54, vcc, s92, v54
	s_nop 1
	v_addc_co_u32_e32 v55, vcc, 0, v55, vcc
	global_load_dwordx4 v[116:119], v[54:55], off offset:512
	v_bitop3_b32 v54, v66, s16, v27 bitop3:0x32
	v_mov_b32_e32 v55, v205
	v_lshlrev_b64 v[54:55], s10, v[54:55]
	v_lshl_add_u64 v[54:55], v[204:205], 0, v[54:55]
	v_add_u32_e32 v204, s9, v5
	v_or_b32_e32 v5, s5, v70
	v_lshrrev_b32_e32 v5, s11, v5
	v_mad_u64_u32 v[90:91], s[18:19], v54, s81, v[52:53]
	v_mov_b32_e32 v54, v91
	v_mad_u64_u32 v[54:55], s[18:19], v55, s81, v[54:55]
	v_mov_b32_e32 v91, v54
	v_lshl_add_u64 v[54:55], v[90:91], 0, s[6:7]
	v_lshl_add_u64 v[54:55], v[54:55], 0, v[16:17]
	v_add_co_u32_e32 v54, vcc, s92, v54
	s_nop 1
	v_addc_co_u32_e32 v55, vcc, 0, v55, vcc
	global_load_dwordx4 v[120:123], v[54:55], off offset:512
	v_bitop3_b32 v54, v68, s16, v27 bitop3:0x32
	v_mov_b32_e32 v55, v205
	v_lshlrev_b64 v[54:55], s10, v[54:55]
	v_lshl_add_u64 v[54:55], v[204:205], 0, v[54:55]
	v_add_u32_e32 v204, s9, v5
	v_or_b32_e32 v5, s5, v72
	v_lshrrev_b32_e32 v5, s11, v5
	v_mad_u64_u32 v[90:91], s[18:19], v54, s81, v[52:53]
	v_mov_b32_e32 v54, v91
	v_mad_u64_u32 v[54:55], s[18:19], v55, s81, v[54:55]
	v_mov_b32_e32 v91, v54
	v_lshl_add_u64 v[54:55], v[90:91], 0, s[6:7]
	v_lshl_add_u64 v[54:55], v[54:55], 0, v[18:19]
	v_add_co_u32_e32 v54, vcc, s92, v54
	s_nop 1
	v_addc_co_u32_e32 v55, vcc, 0, v55, vcc
	global_load_dwordx4 v[124:127], v[54:55], off offset:512
	v_bitop3_b32 v54, v70, s16, v27 bitop3:0x32
	v_mov_b32_e32 v55, v205
	v_lshlrev_b64 v[54:55], s10, v[54:55]
	v_lshl_add_u64 v[54:55], v[204:205], 0, v[54:55]
	v_add_u32_e32 v204, s9, v5
	v_or_b32_e32 v5, s5, v74
	v_lshrrev_b32_e32 v5, s11, v5
	v_mad_u64_u32 v[90:91], s[18:19], v54, s81, v[52:53]
	v_mov_b32_e32 v54, v91
	v_mad_u64_u32 v[54:55], s[18:19], v55, s81, v[54:55]
	v_mov_b32_e32 v91, v54
	v_lshl_add_u64 v[54:55], v[90:91], 0, s[6:7]
	v_lshl_add_u64 v[54:55], v[54:55], 0, v[20:21]
	v_add_co_u32_e32 v54, vcc, s92, v54
	s_nop 1
	v_addc_co_u32_e32 v55, vcc, 0, v55, vcc
	global_load_dwordx4 v[128:131], v[54:55], off offset:512
	v_bitop3_b32 v54, v72, s16, v27 bitop3:0x32
	v_mov_b32_e32 v55, v205
	v_lshlrev_b64 v[54:55], s10, v[54:55]
	v_lshl_add_u64 v[54:55], v[204:205], 0, v[54:55]
	v_add_u32_e32 v204, s9, v5
	v_or_b32_e32 v5, s5, v76
	v_lshrrev_b32_e32 v5, s11, v5
	v_mad_u64_u32 v[90:91], s[18:19], v54, s81, v[52:53]
	v_mov_b32_e32 v54, v91
	v_mad_u64_u32 v[54:55], s[18:19], v55, s81, v[54:55]
	v_mov_b32_e32 v91, v54
	v_lshl_add_u64 v[54:55], v[90:91], 0, s[6:7]
	v_lshl_add_u64 v[54:55], v[54:55], 0, v[22:23]
	v_add_co_u32_e32 v54, vcc, s92, v54
	s_nop 1
	v_addc_co_u32_e32 v55, vcc, 0, v55, vcc
	global_load_dwordx4 v[132:135], v[54:55], off offset:512
	v_bitop3_b32 v54, v74, s16, v27 bitop3:0x32
	v_mov_b32_e32 v55, v205
	v_lshlrev_b64 v[54:55], s10, v[54:55]
	v_lshl_add_u64 v[54:55], v[204:205], 0, v[54:55]
	v_add_u32_e32 v204, s9, v5
	s_add_i32 s9, s9, s5
	v_mad_u64_u32 v[90:91], s[18:19], v54, s81, v[52:53]
	v_mov_b32_e32 v54, v91
	v_mad_u64_u32 v[54:55], s[18:19], v55, s81, v[54:55]
	v_mov_b32_e32 v91, v54
	v_lshl_add_u64 v[54:55], v[90:91], 0, s[6:7]
	v_lshl_add_u64 v[54:55], v[54:55], 0, v[24:25]
	v_add_co_u32_e32 v54, vcc, s92, v54
	s_lshr_b32 s3, s9, 5
	s_nop 0
	v_addc_co_u32_e32 v55, vcc, 0, v55, vcc
	global_load_dwordx4 v[136:139], v[54:55], off offset:512
	v_bitop3_b32 v54, v76, s16, v27 bitop3:0x32
	v_mov_b32_e32 v55, v205
	v_lshlrev_b64 v[54:55], s10, v[54:55]
	v_lshl_add_u64 v[54:55], v[204:205], 0, v[54:55]
	v_mad_u64_u32 v[52:53], s[10:11], v54, s81, v[52:53]
	v_mov_b32_e32 v54, v53
	v_mad_u64_u32 v[54:55], s[10:11], v55, s81, v[54:55]
	v_mov_b32_e32 v53, v54
	v_lshl_add_u64 v[52:53], v[52:53], 0, s[6:7]
	v_mov_b32_e32 v27, v205
	v_lshl_add_u64 v[52:53], v[52:53], 0, v[26:27]
	v_add_co_u32_e32 v52, vcc, s92, v52
	s_nop 1
	v_addc_co_u32_e32 v53, vcc, 0, v53, vcc
	global_load_dwordx4 v[140:143], v[52:53], off offset:512
	s_waitcnt vmcnt(11)
	ds_write_b16 v3, v96
	ds_write_b16_d16_hi v3, v96 offset:144
	ds_write_b16 v3, v97 offset:288
	ds_write_b16_d16_hi v3, v97 offset:432
	ds_write_b16 v3, v98 offset:576
	ds_write_b16_d16_hi v3, v98 offset:720
	ds_write_b16 v3, v99 offset:864
	ds_write_b16_d16_hi v3, v99 offset:1008
	s_waitcnt vmcnt(10)
	ds_write_b16 v57, v100
	ds_write_b16_d16_hi v57, v100 offset:144
	ds_write_b16 v57, v101 offset:288
	ds_write_b16_d16_hi v57, v101 offset:432
	ds_write_b16 v57, v102 offset:576
	ds_write_b16_d16_hi v57, v102 offset:720
	ds_write_b16 v57, v103 offset:864
	ds_write_b16_d16_hi v57, v103 offset:1008
	s_waitcnt vmcnt(9)
	ds_write_b16 v59, v104
	ds_write_b16_d16_hi v59, v104 offset:144
	ds_write_b16 v59, v105 offset:288
	ds_write_b16_d16_hi v59, v105 offset:432
	ds_write_b16 v59, v106 offset:576
	ds_write_b16_d16_hi v59, v106 offset:720
	ds_write_b16 v59, v107 offset:864
	ds_write_b16_d16_hi v59, v107 offset:1008
	s_waitcnt vmcnt(8)
	ds_write_b16 v61, v108
	ds_write_b16_d16_hi v61, v108 offset:144
	ds_write_b16 v61, v109 offset:288
	ds_write_b16_d16_hi v61, v109 offset:432
	ds_write_b16 v61, v110 offset:576
	ds_write_b16_d16_hi v61, v110 offset:720
	ds_write_b16 v61, v111 offset:864
	ds_write_b16_d16_hi v61, v111 offset:1008
	s_waitcnt vmcnt(7)
	ds_write_b16 v63, v112
	ds_write_b16_d16_hi v63, v112 offset:144
	ds_write_b16 v63, v113 offset:288
	ds_write_b16_d16_hi v63, v113 offset:432
	ds_write_b16 v63, v114 offset:576
	ds_write_b16_d16_hi v63, v114 offset:720
	ds_write_b16 v63, v115 offset:864
	ds_write_b16_d16_hi v63, v115 offset:1008
	s_waitcnt vmcnt(6)
	ds_write_b16 v65, v116
	ds_write_b16_d16_hi v65, v116 offset:144
	ds_write_b16 v65, v117 offset:288
	ds_write_b16_d16_hi v65, v117 offset:432
	ds_write_b16 v65, v118 offset:576
	ds_write_b16_d16_hi v65, v118 offset:720
	ds_write_b16 v65, v119 offset:864
	ds_write_b16_d16_hi v65, v119 offset:1008
	s_waitcnt vmcnt(5)
	ds_write_b16 v67, v120
	ds_write_b16_d16_hi v67, v120 offset:144
	ds_write_b16 v67, v121 offset:288
	ds_write_b16_d16_hi v67, v121 offset:432
	ds_write_b16 v67, v122 offset:576
	ds_write_b16_d16_hi v67, v122 offset:720
	ds_write_b16 v67, v123 offset:864
	ds_write_b16_d16_hi v67, v123 offset:1008
	s_waitcnt vmcnt(4)
	ds_write_b16 v69, v124
	ds_write_b16_d16_hi v69, v124 offset:144
	ds_write_b16 v69, v125 offset:288
	ds_write_b16_d16_hi v69, v125 offset:432
	ds_write_b16 v69, v126 offset:576
	ds_write_b16_d16_hi v69, v126 offset:720
	ds_write_b16 v69, v127 offset:864
	ds_write_b16_d16_hi v69, v127 offset:1008
	s_waitcnt vmcnt(3)
	ds_write_b16 v71, v128
	ds_write_b16_d16_hi v71, v128 offset:144
	ds_write_b16 v71, v129 offset:288
	ds_write_b16_d16_hi v71, v129 offset:432
	ds_write_b16 v71, v130 offset:576
	ds_write_b16_d16_hi v71, v130 offset:720
	ds_write_b16 v71, v131 offset:864
	ds_write_b16_d16_hi v71, v131 offset:1008
	s_waitcnt vmcnt(2)
	ds_write_b16 v73, v132
	ds_write_b16_d16_hi v73, v132 offset:144
	ds_write_b16 v73, v133 offset:288
	ds_write_b16_d16_hi v73, v133 offset:432
	ds_write_b16 v73, v134 offset:576
	ds_write_b16_d16_hi v73, v134 offset:720
	ds_write_b16 v73, v135 offset:864
	ds_write_b16_d16_hi v73, v135 offset:1008
	s_waitcnt vmcnt(1)
	ds_write_b16 v75, v136
	ds_write_b16_d16_hi v75, v136 offset:144
	ds_write_b16 v75, v137 offset:288
	ds_write_b16_d16_hi v75, v137 offset:432
	ds_write_b16 v75, v138 offset:576
	ds_write_b16_d16_hi v75, v138 offset:720
	ds_write_b16 v75, v139 offset:864
	ds_write_b16_d16_hi v75, v139 offset:1008
	s_waitcnt vmcnt(0)
	ds_write_b16 v77, v140
	ds_write_b16_d16_hi v77, v140 offset:144
	ds_write_b16 v77, v141 offset:288
	ds_write_b16_d16_hi v77, v141 offset:432
	ds_write_b16 v77, v142 offset:576
	ds_write_b16_d16_hi v77, v142 offset:720
	ds_write_b16 v77, v143 offset:864
	ds_write_b16_d16_hi v77, v143 offset:1008
	s_waitcnt lgkmcnt(0)
	ds_read_b128 v[96:99], v78
	ds_read_b128 v[100:103], v79
	ds_read_b128 v[104:107], v80
	ds_read_b128 v[108:111], v81
	ds_read_b128 v[112:115], v82
	ds_read_b128 v[116:119], v83
	ds_read_b128 v[120:123], v84
	ds_read_b128 v[124:127], v85
	ds_read_b128 v[128:131], v86
	ds_read_b128 v[132:135], v87
	ds_read_b128 v[136:139], v88
	ds_read_b128 v[140:143], v89
	v_or_b32_e32 v5, s3, v0
	s_ashr_i32 s5, s4, 31
	s_lshl_b64 s[4:5], s[4:5], 10
	v_lshlrev_b32_e32 v204, 1, v5
	v_lshl_add_u64 v[90:91], v[204:205], 0, s[4:5]
	v_or_b32_e32 v5, v90, v2
	v_mov_b64_e32 v[92:93], s[0:1]
	v_mad_u64_u32 v[92:93], s[4:5], v5, s21, v[92:93]
	v_mad_i32_i24 v93, v91, s21, v93
	v_lshl_add_u64 v[90:91], v[92:93], 0, v[28:29]
	s_waitcnt lgkmcnt(11)
	global_store_dwordx4 v[90:91], v[96:99], off
	v_lshl_add_u64 v[144:145], v[92:93], 0, v[30:31]
	s_cmpk_gt_i32 s22, 0xbff
	s_waitcnt lgkmcnt(10)
	global_store_dwordx4 v[144:145], v[100:103], off
	v_lshl_add_u64 v[90:91], v[92:93], 0, v[32:33]
	s_waitcnt lgkmcnt(9)
	global_store_dwordx4 v[90:91], v[104:107], off
	v_lshl_add_u64 v[144:145], v[92:93], 0, v[34:35]
	s_waitcnt lgkmcnt(8)
	global_store_dwordx4 v[144:145], v[108:111], off
	v_lshl_add_u64 v[90:91], v[92:93], 0, v[36:37]
	s_waitcnt lgkmcnt(7)
	global_store_dwordx4 v[90:91], v[112:115], off offset:1024
	v_lshl_add_u64 v[144:145], v[92:93], 0, v[38:39]
	s_waitcnt lgkmcnt(6)
	global_store_dwordx4 v[144:145], v[116:119], off offset:1024
	v_lshl_add_u64 v[90:91], v[92:93], 0, v[40:41]
	s_waitcnt lgkmcnt(5)
	global_store_dwordx4 v[90:91], v[120:123], off offset:1024
	v_lshl_add_u64 v[144:145], v[92:93], 0, v[42:43]
	s_waitcnt lgkmcnt(4)
	global_store_dwordx4 v[144:145], v[124:127], off offset:1024
	v_lshl_add_u64 v[90:91], v[92:93], 0, v[44:45]
	s_waitcnt lgkmcnt(3)
	global_store_dwordx4 v[90:91], v[128:131], off offset:2048
	v_lshl_add_u64 v[144:145], v[92:93], 0, v[46:47]
	s_waitcnt lgkmcnt(2)
	global_store_dwordx4 v[144:145], v[132:135], off offset:2048
	v_lshl_add_u64 v[90:91], v[92:93], 0, v[48:49]
	s_waitcnt lgkmcnt(1)
	global_store_dwordx4 v[90:91], v[136:139], off offset:2048
	v_lshl_add_u64 v[144:145], v[92:93], 0, v[50:51]
	s_waitcnt lgkmcnt(0)
	global_store_dwordx4 v[144:145], v[140:143], off offset:2048
	s_waitcnt lgkmcnt(0)
	s_cbranch_scc0 .LBB0_379

.LBB0_531:
	s_or_b64 exec, exec, s[72:73]
	v_readlane_b32 s3, v253, 41
	s_waitcnt lgkmcnt(0)
	s_barrier
	v_mov_b32_e32 v0, s3
	ds_read_b32 v0, v0
	s_mov_b64 s[72:73], -1
	s_waitcnt lgkmcnt(0)
	v_readfirstlane_b32 s3, v0
	s_cmpk_gt_i32 s3, 0x2ff
	s_cbranch_scc1 .LBB0_528
	s_lshl_b32 s3, s3, 3
	s_add_i32 s71, s3, s83
	s_abs_i32 s33, s71
	s_mul_hi_u32 s70, s33, s87
	s_mul_i32 s72, s70, s86
	s_ashr_i32 s3, s71, 31
	s_sub_i32 s33, s33, s72
	s_xor_b32 s3, s3, s80
	s_add_i32 s72, s70, 1
	s_sub_i32 s73, s33, s86
	s_cmp_ge_u32 s33, s86
	s_cselect_b32 s70, s72, s70
	s_cselect_b32 s33, s73, s33
	s_add_i32 s72, s70, 1
	s_cmp_ge_u32 s33, s86
	s_cselect_b32 s33, s72, s70
	s_xor_b32 s33, s33, s3
	s_sub_i32 s72, s33, s3
	s_ashr_i32 s3, s72, 2
	s_mul_hi_i32 s33, s3, 0x55555556
	s_lshr_b32 s70, s33, 31
	s_add_i32 s70, s33, s70
	s_mul_i32 s33, s70, 3
	s_sub_i32 s73, s3, s33
	s_lshl_b32 s33, s73, 1
	v_readlane_b32 s4, v252, 9
	s_sub_i32 vcc_lo, s4, s33
	s_lshl_b32 s3, 1, vcc_lo
	s_lshr_b32 s82, s3, 5
	v_cvt_f32_u32_e32 v0, s82
	s_mov_b32 s8, s91
	s_mov_b32 s7, s90
	s_sub_i32 s90, 0, s82
	v_rcp_iflag_f32_e32 v0, v0
	s_mul_i32 s88, s72, s76
	s_sub_i32 s71, s71, s88
	s_mov_b32 s6, s89
	v_mul_f32_e32 v0, 0x4f7ffffe, v0
	v_cvt_u32_f32_e32 v0, v0
	s_abs_i32 s89, s71
	s_and_b32 s88, s72, 3
	s_ashr_i32 s72, s71, 31
	v_readfirstlane_b32 s91, v0
	s_mul_i32 s90, s90, s91
	s_mul_hi_u32 s90, s91, s90
	s_add_i32 s91, s91, s90
	s_mul_hi_u32 s90, s89, s91
	s_mul_i32 s91, s90, s82
	s_sub_i32 s89, s89, s91
	s_add_i32 s91, s90, 1
	s_sub_i32 s92, s89, s82
	s_cmp_ge_u32 s89, s82
	s_cselect_b32 s90, s91, s90
	s_cselect_b32 s89, s92, s89
	s_add_i32 s91, s90, 1
	s_cmp_ge_u32 s89, s82
	s_cselect_b32 s89, s91, s90
	s_xor_b32 s89, s89, s72
	s_sub_i32 s72, s89, s72
	s_mul_i32 s82, s72, s82
	s_sub_i32 s90, s71, s82
	s_lshl_b32 s71, s73, 2
	s_lshl_b32 s82, s90, 5
	s_or_b32 s96, s71, s88
	s_ashr_i32 s71, s70, 31
	s_lshl_b64 s[70:71], s[70:71], s4
	s_ashr_i32 s73, s72, 31
	v_or_b32_e32 v0, s82, v182
	s_add_u32 s94, s70, s72
	v_ashrrev_i32_e32 v1, 31, v0
	s_addc_u32 s95, s71, s73
	v_lshlrev_b64 v[0:1], s33, v[0:1]
	v_lshl_add_u64 v[0:1], v[0:1], 0, s[94:95]
	v_mov_b64_e32 v[178:179], s[84:85]
	v_mad_u64_u32 v[2:3], s[88:89], v0, s81, v[178:179]
	v_mov_b32_e32 v0, v3
	v_mad_u64_u32 v[0:1], s[88:89], v1, s81, v[0:1]
	s_mul_i32 s88, s96, 0x60
	s_ashr_i32 s89, s88, 31
	s_lshl_b64 s[92:93], s[88:89], 1
	s_sub_i32 s4, s82, 64
	s_cmp_gt_i32 s90, 1
	s_cselect_b64 s[88:89], -1, 0
	s_cmp_lt_i32 s4, s3
	s_cselect_b64 s[90:91], -1, 0
	s_and_b64 s[88:89], s[88:89], s[90:91]
	v_mov_b32_e32 v3, v0
	s_and_b64 s[88:89], s[88:89], exec
	v_lshl_add_u64 v[0:1], v[2:3], 0, s[92:93]
	s_cselect_b32 s5, s4, s82
	v_lshl_add_u64 v[132:133], v[0:1], 0, v[204:205]
	v_or_b32_e32 v0, s5, v182
	v_ashrrev_i32_e32 v1, 31, v0
	v_lshlrev_b64 v[0:1], s33, v[0:1]
	v_lshl_add_u64 v[0:1], v[0:1], 0, s[94:95]
	v_mad_u64_u32 v[2:3], s[88:89], v0, s81, v[178:179]
	v_mov_b32_e32 v0, v3
	v_mad_u64_u32 v[0:1], s[88:89], v1, s81, v[0:1]
	s_ashr_i32 s97, s96, 31
	s_lshl_b64 s[88:89], s[96:97], 9
	s_lshl_b64 s[72:73], s[72:73], vcc_lo
	s_add_u32 s70, s72, s70
	s_addc_u32 s71, s73, s71
	s_ashr_i32 s73, s5, 31
	s_add_u32 s72, s70, s5
	s_addc_u32 s73, s71, s73
	v_mov_b32_e32 v3, v0
	s_lshr_b64 s[72:73], s[72:73], 5
	v_lshl_add_u64 v[0:1], v[2:3], 0, s[92:93]
	s_add_u32 s5, s72, s88
	v_lshl_add_u64 v[16:17], v[0:1], 0, v[204:205]
	s_addc_u32 s72, s73, s89
	global_load_dwordx4 v[100:103], v[132:133], off
	global_load_dwordx4 v[96:99], v[132:133], off offset:32
	global_load_dwordx4 v[92:95], v[132:133], off offset:64
	global_load_dwordx4 v[80:83], v[132:133], off offset:96
	global_load_dwordx4 v[84:87], v[132:133], off offset:128
	global_load_dwordx4 v[88:91], v[132:133], off offset:160
	global_load_dwordx4 v[0:3], v[16:17], off offset:2304
	global_load_dwordx4 v[4:7], v[16:17], off offset:2336
	global_load_dwordx4 v[8:11], v[16:17], off offset:2368
	global_load_dwordx4 v[12:15], v[16:17], off offset:2400
	global_load_dwordx4 v[42:45], v[16:17], off offset:2432
	global_load_dwordx4 v[46:49], v[16:17], off offset:2464
	s_mul_i32 s90, s72, 0x1800
	v_mad_u64_u32 v[16:17], s[72:73], s5, v229, v[176:177]
	s_movk_i32 s9, 0x1000
	v_add_u32_e32 v17, s90, v17
	global_load_dwordx4 v[50:53], v[16:17], off
	global_load_dwordx4 v[38:41], v[16:17], off offset:1024
	global_load_dwordx4 v[34:37], v[16:17], off offset:2048
	global_load_dwordx4 v[68:71], v[16:17], off offset:3072
	v_add_co_u32_e32 v16, vcc, s9, v16
	s_nop 1
	v_addc_co_u32_e32 v17, vcc, 0, v17, vcc
	global_load_dwordx4 v[76:79], v[16:17], off
	global_load_dwordx4 v[72:75], v[16:17], off offset:1024
	s_sub_i32 s5, s82, 32
	s_cmp_lt_u32 s5, s3
	s_cselect_b64 vcc, -1, 0
	s_and_b64 s[72:73], vcc, exec
	s_cselect_b32 s5, s5, s82
	v_or_b32_e32 v16, s5, v182
	v_ashrrev_i32_e32 v17, 31, v16
	v_lshlrev_b64 v[16:17], s33, v[16:17]
	v_lshl_add_u64 v[16:17], v[16:17], 0, s[94:95]
	v_mad_u64_u32 v[18:19], s[72:73], v16, s81, v[178:179]
	v_mov_b32_e32 v16, v19
	v_mad_u64_u32 v[16:17], s[72:73], v17, s81, v[16:17]
	s_ashr_i32 s73, s5, 31
	s_add_u32 s72, s70, s5
	s_addc_u32 s73, s71, s73
	v_mov_b32_e32 v19, v16
	s_lshr_b64 s[72:73], s[72:73], 5
	v_lshl_add_u64 v[16:17], v[18:19], 0, s[92:93]
	s_add_u32 s5, s72, s88
	v_lshl_add_u64 v[16:17], v[16:17], 0, v[204:205]
	s_addc_u32 s72, s73, s89
	global_load_dwordx4 v[64:67], v[16:17], off offset:2304
	global_load_dwordx4 v[164:167], v[16:17], off offset:2336
	global_load_dwordx4 v[160:163], v[16:17], off offset:2368
	global_load_dwordx4 v[152:155], v[16:17], off offset:2400
	global_load_dwordx4 v[144:147], v[16:17], off offset:2432
	global_load_dwordx4 v[136:139], v[16:17], off offset:2464
	s_mul_i32 s90, s72, 0x1800
	v_mad_u64_u32 v[16:17], s[72:73], s5, v229, v[176:177]
	v_add_u32_e32 v17, s90, v17
	global_load_dwordx4 v[128:131], v[16:17], off
	global_load_dwordx4 v[124:127], v[16:17], off offset:1024
	global_load_dwordx4 v[120:123], v[16:17], off offset:2048
	global_load_dwordx4 v[108:111], v[16:17], off offset:3072
	v_add_co_u32_e64 v16, s[72:73], s9, v16
	s_nop 1
	v_addc_co_u32_e64 v17, s[72:73], 0, v17, s[72:73]
	global_load_dwordx4 v[116:119], v[16:17], off
	global_load_dwordx4 v[112:115], v[16:17], off offset:1024
	s_waitcnt vmcnt(12)
	v_mfma_f32_32x32x16_bf16 v[18:33], v[0:3], v[100:103], 0
	s_cmp_lt_u32 s4, s3
	v_readlane_b32 s4, v254, 61
	s_cselect_b64 s[90:91], -1, 0
	v_readlane_b32 s5, v254, 62
	s_and_b64 s[72:73], s[90:91], s[4:5]
	v_readlane_b32 s4, v254, 63
	v_readlane_b32 s5, v252, 0
	v_mfma_f32_32x32x16_bf16 v[18:33], v[4:7], v[96:99], v[18:33]
	v_readlane_b32 s16, v254, 4
	v_readlane_b32 s18, v254, 6
	v_readlane_b32 s19, v254, 7
	v_readlane_b32 s17, v254, 5
	s_mov_b32 s18, s16
	s_mov_b32 s19, s16
	s_mov_b32 s17, s16
	v_mfma_f32_32x32x16_bf16 v[18:33], v[8:11], v[92:95], v[18:33]
	v_mov_b64_e32 v[106:107], s[18:19]
	v_mov_b64_e32 v[104:105], s[16:17]
	v_mfma_f32_32x32x16_bf16 v[18:33], v[12:15], v[80:83], v[18:33]
	v_mfma_f32_32x32x16_bf16 v[18:33], v[42:45], v[84:87], v[18:33]
	v_mfma_f32_32x32x16_bf16 v[18:33], v[46:49], v[88:91], v[18:33]
	s_nop 11
	v_add_f32_e32 v0, v180, v18
	v_exp_f32_e32 v0, v0
	v_add_f32_e32 v1, v180, v19
	v_exp_f32_e32 v1, v1
	v_add_f32_e32 v2, v180, v20
	v_exp_f32_e32 v2, v2
	v_cndmask_b32_e64 v0, 0, v0, s[72:73]
	s_and_b64 s[72:73], s[90:91], s[4:5]
	v_readlane_b32 s4, v252, 1
	v_add_f32_e32 v3, v180, v21
	v_readlane_b32 s5, v252, 2
	v_exp_f32_e32 v3, v3
	v_cndmask_b32_e64 v1, 0, v1, s[72:73]
	s_and_b64 s[72:73], s[90:91], s[4:5]
	v_readlane_b32 s4, v252, 3
	v_add_f32_e32 v4, v180, v22
	v_readlane_b32 s5, v252, 4
	v_add_f32_e32 v5, v180, v23
	v_exp_f32_e32 v4, v4
	v_cndmask_b32_e64 v2, 0, v2, s[72:73]
	s_and_b64 s[72:73], s[90:91], s[4:5]
	v_readlane_b32 s4, v252, 5
	v_add_f32_e32 v6, v180, v24
	v_exp_f32_e32 v5, v5
	v_readlane_b32 s5, v252, 6
	v_add_f32_e32 v7, v180, v25
	v_exp_f32_e32 v6, v6
	v_cndmask_b32_e64 v3, 0, v3, s[72:73]
	s_and_b64 s[72:73], s[90:91], s[4:5]
	v_readlane_b32 s4, v252, 7
	v_add_f32_e32 v8, v180, v26
	v_exp_f32_e32 v7, v7
	v_readlane_b32 s5, v252, 8
	v_add_f32_e32 v9, v180, v27
	v_exp_f32_e32 v8, v8
	v_cndmask_b32_e64 v4, 0, v4, s[72:73]
	s_and_b64 s[72:73], s[90:91], s[4:5]
	v_add_f32_e32 v10, v180, v28
	v_exp_f32_e32 v9, v9
	v_cndmask_b32_e64 v5, 0, v5, s[72:73]
	s_and_b64 s[72:73], s[90:91], s[10:11]
	v_exp_f32_e32 v16, v10
	v_cndmask_b32_e64 v6, 0, v6, s[72:73]
	s_and_b64 s[72:73], s[90:91], s[14:15]
	v_cndmask_b32_e64 v7, 0, v7, s[72:73]
	s_and_b64 s[72:73], s[90:91], s[20:21]
	v_cndmask_b32_e64 v134, 0, v8, s[72:73]
	s_and_b64 s[72:73], s[90:91], s[22:23]
	v_add_f32_e32 v11, v180, v29
	v_cndmask_b32_e64 v135, 0, v9, s[72:73]
	s_and_b64 s[72:73], s[90:91], s[24:25]
	v_exp_f32_e32 v17, v11
	v_cndmask_b32_e64 v141, 0, v16, s[72:73]
	v_add_f32_e32 v16, v180, v30
	v_exp_f32_e32 v42, v16
	v_add_f32_e32 v16, v180, v31
	v_exp_f32_e32 v43, v16
	v_add_f32_e32 v32, v180, v32
	v_cvt_pk_bf16_f32 v54, v0, v1
	v_cvt_pk_bf16_f32 v55, v2, v3
	v_cvt_pk_bf16_f32 v56, v4, v5
	v_cvt_pk_bf16_f32 v57, v6, v7
	s_and_b64 s[72:73], s[90:91], s[26:27]
	v_exp_f32_e32 v48, v32
	v_add_f32_e32 v32, v180, v33
	v_cndmask_b32_e64 v142, 0, v17, s[72:73]
	s_and_b64 s[72:73], s[90:91], s[28:29]
	v_exp_f32_e32 v49, v32
	v_cndmask_b32_e64 v143, 0, v42, s[72:73]
	s_and_b64 s[72:73], s[90:91], s[30:31]
	v_cndmask_b32_e64 v148, 0, v43, s[72:73]
	s_and_b64 s[72:73], s[90:91], s[34:35]
	v_cndmask_b32_e64 v149, 0, v48, s[72:73]
	s_and_b64 s[72:73], s[90:91], s[36:37]
	v_mfma_f32_32x32x16_bf16 v[0:15], v[54:57], v[50:53], 0
	v_cndmask_b32_e64 v150, 0, v49, s[72:73]
	v_cvt_pk_bf16_f32 v140, v134, v135
	v_cvt_pk_bf16_f32 v141, v141, v142
	v_cvt_pk_bf16_f32 v142, v143, v148
	v_cvt_pk_bf16_f32 v143, v149, v150
	s_mov_b32 s4, s16
	v_writelane_b32 v254, s4, 4
	v_mfma_f32_32x32x16_bf16 v[16:31], v[54:57], v[38:41], 0
	s_nop 0
	v_writelane_b32 v254, s5, 5
	v_writelane_b32 v254, s6, 6
	v_writelane_b32 v254, s7, 7
	v_mfma_f32_32x32x16_bf16 v[32:47], v[54:57], v[34:37], 0
	v_mfma_f32_32x32x16_bf16 v[48:63], v[54:57], v[104:107], 0
	v_mfma_f32_32x32x16_bf16 v[0:15], v[140:143], v[68:71], v[0:15]
	v_mfma_f32_32x32x16_bf16 v[16:31], v[140:143], v[76:79], v[16:31]
	v_mfma_f32_32x32x16_bf16 v[32:47], v[140:143], v[72:75], v[32:47]
	v_mfma_f32_32x32x16_bf16 v[48:63], v[140:143], v[104:107], v[48:63]
	s_ashr_i32 s4, s82, 31
	s_add_u32 s72, s70, s82
	s_addc_u32 s73, s71, s4
	s_lshr_b64 s[72:73], s[72:73], 5
	s_add_u32 s4, s72, s88
	s_addc_u32 s5, s73, s89
	global_load_dwordx4 v[184:187], v[132:133], off offset:2304
	global_load_dwordx4 v[188:191], v[132:133], off offset:2336
	global_load_dwordx4 v[192:195], v[132:133], off offset:2368
	global_load_dwordx4 v[196:199], v[132:133], off offset:2400
	global_load_dwordx4 v[200:203], v[132:133], off offset:2432
	global_load_dwordx4 v[214:217], v[132:133], off offset:2464
	s_mulk_i32 s5, 0x1800
	v_mad_u64_u32 v[68:69], s[72:73], s4, v229, v[176:177]
	v_add_u32_e32 v69, s5, v69
	global_load_dwordx4 v[172:175], v[68:69], off
	global_load_dwordx4 v[168:171], v[68:69], off offset:1024
	global_load_dwordx4 v[156:159], v[68:69], off offset:2048
	global_load_dwordx4 v[132:135], v[68:69], off offset:3072
	v_add_co_u32_e64 v68, s[72:73], s9, v68
	s_nop 1
	v_addc_co_u32_e64 v69, s[72:73], 0, v69, s[72:73]
	global_load_dwordx4 v[148:151], v[68:69], off
	global_load_dwordx4 v[140:143], v[68:69], off offset:1024
	s_waitcnt vmcnt(23)
	v_mfma_f32_32x32x16_bf16 v[64:79], v[64:67], v[100:103], 0
	s_waitcnt vmcnt(22)
	v_mfma_f32_32x32x16_bf16 v[64:79], v[164:167], v[96:99], v[64:79]
	s_waitcnt vmcnt(21)
	v_mfma_f32_32x32x16_bf16 v[64:79], v[160:163], v[92:95], v[64:79]
	s_waitcnt vmcnt(20)
	v_mfma_f32_32x32x16_bf16 v[64:79], v[152:155], v[80:83], v[64:79]
	s_waitcnt vmcnt(19)
	v_mfma_f32_32x32x16_bf16 v[64:79], v[144:147], v[84:87], v[64:79]
	s_waitcnt vmcnt(18)
	v_mfma_f32_32x32x16_bf16 v[64:79], v[136:139], v[88:91], v[64:79]
	s_nop 11
	v_add_f32_e32 v64, v180, v64
	v_add_f32_e32 v65, v180, v65
	v_add_f32_e32 v66, v180, v66
	v_add_f32_e32 v67, v180, v67
	v_add_f32_e32 v68, v180, v68
	v_add_f32_e32 v69, v180, v69
	v_add_f32_e32 v70, v180, v70
	v_add_f32_e32 v71, v180, v71
	v_exp_f32_e32 v64, v64
	v_exp_f32_e32 v65, v65
	v_exp_f32_e32 v66, v66
	v_exp_f32_e32 v67, v67
	v_exp_f32_e32 v68, v68
	v_exp_f32_e32 v69, v69
	v_exp_f32_e32 v70, v70
	v_exp_f32_e32 v71, v71
	v_cndmask_b32_e32 v64, 0, v64, vcc
	v_cndmask_b32_e32 v65, 0, v65, vcc
	v_cndmask_b32_e32 v66, 0, v66, vcc
	v_cndmask_b32_e32 v67, 0, v67, vcc
	v_cndmask_b32_e32 v68, 0, v68, vcc
	v_cndmask_b32_e32 v69, 0, v69, vcc
	v_cndmask_b32_e32 v70, 0, v70, vcc
	v_cndmask_b32_e32 v71, 0, v71, vcc
	v_cvt_pk_bf16_f32 v64, v64, v65
	v_cvt_pk_bf16_f32 v65, v66, v67
	v_cvt_pk_bf16_f32 v66, v68, v69
	v_cvt_pk_bf16_f32 v67, v70, v71
	v_add_f32_e32 v68, v180, v72
	v_add_f32_e32 v69, v180, v73
	v_add_f32_e32 v70, v180, v74
	v_add_f32_e32 v71, v180, v75
	v_add_f32_e32 v72, v180, v76
	v_add_f32_e32 v73, v180, v77
	v_add_f32_e32 v74, v180, v78
	v_add_f32_e32 v75, v180, v79
	v_exp_f32_e32 v68, v68
	v_exp_f32_e32 v69, v69
	v_exp_f32_e32 v70, v70
	v_exp_f32_e32 v71, v71
	v_exp_f32_e32 v72, v72
	v_exp_f32_e32 v73, v73
	v_exp_f32_e32 v74, v74
	v_exp_f32_e32 v75, v75
	s_waitcnt vmcnt(17)
	v_mfma_f32_32x32x16_bf16 v[0:15], v[64:67], v[128:131], v[0:15]
	v_cndmask_b32_e32 v68, 0, v68, vcc
	v_cndmask_b32_e32 v69, 0, v69, vcc
	v_cndmask_b32_e32 v70, 0, v70, vcc
	v_cndmask_b32_e32 v71, 0, v71, vcc
	v_cndmask_b32_e32 v72, 0, v72, vcc
	v_cndmask_b32_e32 v73, 0, v73, vcc
	v_cndmask_b32_e32 v74, 0, v74, vcc
	s_waitcnt vmcnt(16)
	v_mfma_f32_32x32x16_bf16 v[16:31], v[64:67], v[124:127], v[16:31]
	v_cndmask_b32_e32 v75, 0, v75, vcc
	s_waitcnt vmcnt(15)
	v_mfma_f32_32x32x16_bf16 v[32:47], v[64:67], v[120:123], v[32:47]
	v_mfma_f32_32x32x16_bf16 v[48:63], v[64:67], v[104:107], v[48:63]
	v_cvt_pk_bf16_f32 v64, v68, v69
	v_cvt_pk_bf16_f32 v65, v70, v71
	v_cvt_pk_bf16_f32 v66, v72, v73
	v_cvt_pk_bf16_f32 v67, v74, v75
	s_waitcnt vmcnt(14)
	s_nop 0
	v_mfma_f32_32x32x16_bf16 v[0:15], v[64:67], v[108:111], v[0:15]
	s_waitcnt vmcnt(13)
	v_mfma_f32_32x32x16_bf16 v[16:31], v[64:67], v[116:119], v[16:31]
	s_waitcnt vmcnt(12)
	v_mfma_f32_32x32x16_bf16 v[32:47], v[64:67], v[112:115], v[32:47]
	v_mfma_f32_32x32x16_bf16 v[48:63], v[64:67], v[104:107], v[48:63]
	s_add_i32 s4, s82, 32
	s_cmp_lt_u32 s4, s3
	s_cselect_b64 vcc, -1, 0
	s_and_b64 s[72:73], vcc, exec
	s_cselect_b32 s4, s4, s82
	v_or_b32_e32 v64, s4, v182
	v_ashrrev_i32_e32 v65, 31, v64
	v_lshlrev_b64 v[64:65], s33, v[64:65]
	v_lshl_add_u64 v[64:65], v[64:65], 0, s[94:95]
	v_mad_u64_u32 v[66:67], s[72:73], v64, s81, v[178:179]
	v_mov_b32_e32 v64, v67
	v_mad_u64_u32 v[64:65], s[72:73], v65, s81, v[64:65]
	s_ashr_i32 s5, s4, 31
	s_add_u32 s72, s70, s4
	s_addc_u32 s73, s71, s5
	v_mov_b32_e32 v67, v64
	s_lshr_b64 s[72:73], s[72:73], 5
	v_lshl_add_u64 v[64:65], v[66:67], 0, s[92:93]
	s_add_u32 s4, s72, s88
	v_lshl_add_u64 v[64:65], v[64:65], 0, v[204:205]
	s_addc_u32 s5, s73, s89
	global_load_dwordx4 v[232:235], v[64:65], off offset:2304
	global_load_dwordx4 v[236:239], v[64:65], off offset:2336
	global_load_dwordx4 v[240:243], v[64:65], off offset:2368
	global_load_dwordx4 v[244:247], v[64:65], off offset:2400
	global_load_dwordx4 v[248:251], v[64:65], off offset:2432
	global_load_dwordx4 v[206:209], v[64:65], off offset:2464
	s_mulk_i32 s5, 0x1800
	v_mad_u64_u32 v[64:65], s[72:73], s4, v229, v[176:177]
	v_add_u32_e32 v65, s5, v65
	global_load_dwordx4 v[164:167], v[64:65], off
	global_load_dwordx4 v[160:163], v[64:65], off offset:1024
	global_load_dwordx4 v[152:155], v[64:65], off offset:2048
	global_load_dwordx4 v[128:131], v[64:65], off offset:3072
	v_add_co_u32_e64 v64, s[72:73], s9, v64
	s_nop 1
	v_addc_co_u32_e64 v65, s[72:73], 0, v65, s[72:73]
	global_load_dwordx4 v[144:147], v[64:65], off
	global_load_dwordx4 v[136:139], v[64:65], off offset:1024
	s_waitcnt vmcnt(23)
	v_mfma_f32_32x32x16_bf16 v[64:79], v[184:187], v[100:103], 0
	s_cmp_lt_u32 s82, s3
	s_cselect_b64 s[72:73], -1, 0
	s_waitcnt vmcnt(22)
	v_mfma_f32_32x32x16_bf16 v[64:79], v[188:191], v[96:99], v[64:79]
	s_waitcnt vmcnt(21)
	v_mfma_f32_32x32x16_bf16 v[64:79], v[192:195], v[92:95], v[64:79]
	s_waitcnt vmcnt(20)
	v_mfma_f32_32x32x16_bf16 v[64:79], v[196:199], v[80:83], v[64:79]
	s_waitcnt vmcnt(19)
	v_mfma_f32_32x32x16_bf16 v[64:79], v[200:203], v[84:87], v[64:79]
	s_waitcnt vmcnt(18)
	v_mfma_f32_32x32x16_bf16 v[64:79], v[214:217], v[88:91], v[64:79]
	s_nop 11
	v_add_f32_e32 v64, v180, v64
	v_add_f32_e32 v65, v180, v65
	v_add_f32_e32 v66, v180, v66
	v_add_f32_e32 v67, v180, v67
	v_add_f32_e32 v68, v180, v68
	v_add_f32_e32 v69, v180, v69
	v_add_f32_e32 v70, v180, v70
	v_add_f32_e32 v71, v180, v71
	v_exp_f32_e32 v64, v64
	v_exp_f32_e32 v65, v65
	v_exp_f32_e32 v66, v66
	v_exp_f32_e32 v67, v67
	v_exp_f32_e32 v68, v68
	v_exp_f32_e32 v69, v69
	v_exp_f32_e32 v70, v70
	v_exp_f32_e32 v71, v71
	v_cndmask_b32_e64 v64, 0, v64, s[72:73]
	v_cndmask_b32_e64 v65, 0, v65, s[72:73]
	v_cndmask_b32_e64 v66, 0, v66, s[72:73]
	v_cndmask_b32_e64 v67, 0, v67, s[72:73]
	v_cndmask_b32_e64 v68, 0, v68, s[72:73]
	v_cndmask_b32_e64 v69, 0, v69, s[72:73]
	v_cndmask_b32_e64 v70, 0, v70, s[72:73]
	v_cndmask_b32_e64 v71, 0, v71, s[72:73]
	v_cvt_pk_bf16_f32 v64, v64, v65
	v_cvt_pk_bf16_f32 v65, v66, v67
	v_cvt_pk_bf16_f32 v66, v68, v69
	v_cvt_pk_bf16_f32 v67, v70, v71
	v_add_f32_e32 v68, v180, v72
	v_add_f32_e32 v69, v180, v73
	v_add_f32_e32 v70, v180, v74
	v_add_f32_e32 v71, v180, v75
	v_add_f32_e32 v72, v180, v76
	v_add_f32_e32 v73, v180, v77
	v_add_f32_e32 v74, v180, v78
	v_add_f32_e32 v75, v180, v79
	v_exp_f32_e32 v68, v68
	v_exp_f32_e32 v69, v69
	v_exp_f32_e32 v70, v70
	v_exp_f32_e32 v71, v71
	v_exp_f32_e32 v72, v72
	v_exp_f32_e32 v73, v73
	v_exp_f32_e32 v74, v74
	v_exp_f32_e32 v75, v75
	s_waitcnt vmcnt(17)
	v_mfma_f32_32x32x16_bf16 v[0:15], v[64:67], v[172:175], v[0:15]
	v_cndmask_b32_e64 v68, 0, v68, s[72:73]
	v_cndmask_b32_e64 v69, 0, v69, s[72:73]
	v_cndmask_b32_e64 v70, 0, v70, s[72:73]
	v_cndmask_b32_e64 v71, 0, v71, s[72:73]
	v_cndmask_b32_e64 v72, 0, v72, s[72:73]
	v_cndmask_b32_e64 v73, 0, v73, s[72:73]
	v_cndmask_b32_e64 v74, 0, v74, s[72:73]
	s_waitcnt vmcnt(16)
	v_mfma_f32_32x32x16_bf16 v[16:31], v[64:67], v[168:171], v[16:31]
	v_cndmask_b32_e64 v75, 0, v75, s[72:73]
	s_waitcnt vmcnt(15)
	v_mfma_f32_32x32x16_bf16 v[32:47], v[64:67], v[156:159], v[32:47]
	v_mfma_f32_32x32x16_bf16 v[48:63], v[64:67], v[104:107], v[48:63]
	v_cvt_pk_bf16_f32 v64, v68, v69
	v_cvt_pk_bf16_f32 v65, v70, v71
	v_cvt_pk_bf16_f32 v66, v72, v73
	v_cvt_pk_bf16_f32 v67, v74, v75
	s_waitcnt vmcnt(14)
	s_nop 0
	v_mfma_f32_32x32x16_bf16 v[0:15], v[64:67], v[132:135], v[0:15]
	s_waitcnt vmcnt(13)
	v_mfma_f32_32x32x16_bf16 v[16:31], v[64:67], v[148:151], v[16:31]
	s_waitcnt vmcnt(12)
	v_mfma_f32_32x32x16_bf16 v[32:47], v[64:67], v[140:143], v[32:47]
	v_mfma_f32_32x32x16_bf16 v[48:63], v[64:67], v[104:107], v[48:63]
	s_add_i32 s4, s82, 64
	s_cmp_lt_u32 s4, s3
	s_cselect_b64 s[90:91], -1, 0
	s_and_b64 s[72:73], s[90:91], exec
	s_cselect_b32 s3, s4, s82
	v_or_b32_e32 v64, s3, v182
	v_ashrrev_i32_e32 v65, 31, v64
	v_lshlrev_b64 v[64:65], s33, v[64:65]
	v_lshl_add_u64 v[64:65], v[64:65], 0, s[94:95]
	v_mad_u64_u32 v[66:67], s[72:73], v64, s81, v[178:179]
	s_ashr_i32 s4, s3, 31
	v_mov_b32_e32 v64, v67
	s_add_u32 s70, s70, s3
	v_mad_u64_u32 v[64:65], s[72:73], v65, s81, v[64:65]
	s_addc_u32 s71, s71, s4
	v_mov_b32_e32 v67, v64
	s_lshr_b64 s[70:71], s[70:71], 5
	v_lshl_add_u64 v[64:65], v[66:67], 0, s[92:93]
	s_add_u32 s3, s70, s88
	v_lshl_add_u64 v[64:65], v[64:65], 0, v[204:205]
	s_addc_u32 s4, s71, s89
	global_load_dwordx4 v[140:143], v[64:65], off offset:2304
	global_load_dwordx4 v[148:151], v[64:65], off offset:2336
	global_load_dwordx4 v[156:159], v[64:65], off offset:2368
	global_load_dwordx4 v[168:171], v[64:65], off offset:2400
	global_load_dwordx4 v[172:175], v[64:65], off offset:2432
	global_load_dwordx4 v[184:187], v[64:65], off offset:2464
	s_mulk_i32 s4, 0x1800
	v_mad_u64_u32 v[64:65], s[70:71], s3, v229, v[176:177]
	v_add_u32_e32 v65, s4, v65
	global_load_dwordx4 v[132:135], v[64:65], off
	global_load_dwordx4 v[124:127], v[64:65], off offset:1024
	global_load_dwordx4 v[120:123], v[64:65], off offset:2048
	global_load_dwordx4 v[108:111], v[64:65], off offset:3072
	v_add_co_u32_e64 v64, s[72:73], s9, v64
	s_nop 1
	v_addc_co_u32_e64 v65, s[72:73], 0, v65, s[72:73]
	global_load_dwordx4 v[116:119], v[64:65], off
	global_load_dwordx4 v[112:115], v[64:65], off offset:1024
	s_waitcnt vmcnt(23)
	v_mfma_f32_32x32x16_bf16 v[64:79], v[232:235], v[100:103], 0
	s_waitcnt vmcnt(22)
	v_mfma_f32_32x32x16_bf16 v[64:79], v[236:239], v[96:99], v[64:79]
	s_waitcnt vmcnt(21)
	v_mfma_f32_32x32x16_bf16 v[64:79], v[240:243], v[92:95], v[64:79]
	s_waitcnt vmcnt(20)
	v_mfma_f32_32x32x16_bf16 v[64:79], v[244:247], v[80:83], v[64:79]
	s_waitcnt vmcnt(19)
	v_mfma_f32_32x32x16_bf16 v[64:79], v[248:251], v[84:87], v[64:79]
	s_waitcnt vmcnt(18)
	v_mfma_f32_32x32x16_bf16 v[64:79], v[206:209], v[88:91], v[64:79]
	s_nop 11
	v_add_f32_e32 v64, v180, v64
	v_add_f32_e32 v65, v180, v65
	v_add_f32_e32 v66, v180, v66
	v_add_f32_e32 v67, v180, v67
	v_add_f32_e32 v68, v180, v68
	v_add_f32_e32 v69, v180, v69
	v_add_f32_e32 v70, v180, v70
	v_add_f32_e32 v71, v180, v71
	v_exp_f32_e32 v64, v64
	v_exp_f32_e32 v65, v65
	v_exp_f32_e32 v66, v66
	v_exp_f32_e32 v67, v67
	v_exp_f32_e32 v68, v68
	v_exp_f32_e32 v69, v69
	v_exp_f32_e32 v70, v70
	v_exp_f32_e32 v71, v71
	v_cndmask_b32_e32 v64, 0, v64, vcc
	v_cndmask_b32_e32 v65, 0, v65, vcc
	v_cndmask_b32_e32 v66, 0, v66, vcc
	v_cndmask_b32_e32 v67, 0, v67, vcc
	v_cndmask_b32_e32 v68, 0, v68, vcc
	v_cndmask_b32_e32 v69, 0, v69, vcc
	v_cndmask_b32_e32 v70, 0, v70, vcc
	v_cndmask_b32_e32 v71, 0, v71, vcc
	v_cvt_pk_bf16_f32 v64, v64, v65
	v_cvt_pk_bf16_f32 v65, v66, v67
	v_cvt_pk_bf16_f32 v66, v68, v69
	v_cvt_pk_bf16_f32 v67, v70, v71
	v_add_f32_e32 v68, v180, v72
	v_add_f32_e32 v69, v180, v73
	v_add_f32_e32 v70, v180, v74
	v_add_f32_e32 v71, v180, v75
	v_add_f32_e32 v72, v180, v76
	v_add_f32_e32 v73, v180, v77
	v_add_f32_e32 v74, v180, v78
	v_add_f32_e32 v75, v180, v79
	v_exp_f32_e32 v68, v68
	v_exp_f32_e32 v69, v69
	v_exp_f32_e32 v70, v70
	v_exp_f32_e32 v71, v71
	v_exp_f32_e32 v72, v72
	v_exp_f32_e32 v73, v73
	v_exp_f32_e32 v74, v74
	v_exp_f32_e32 v75, v75
	s_waitcnt vmcnt(17)
	v_mfma_f32_32x32x16_bf16 v[0:15], v[64:67], v[164:167], v[0:15]
	v_cndmask_b32_e32 v68, 0, v68, vcc
	v_cndmask_b32_e32 v69, 0, v69, vcc
	v_cndmask_b32_e32 v70, 0, v70, vcc
	v_cndmask_b32_e32 v71, 0, v71, vcc
	v_cndmask_b32_e32 v72, 0, v72, vcc
	v_cndmask_b32_e32 v73, 0, v73, vcc
	v_cndmask_b32_e32 v74, 0, v74, vcc
	s_waitcnt vmcnt(16)
	v_mfma_f32_32x32x16_bf16 v[16:31], v[64:67], v[160:163], v[16:31]
	v_cndmask_b32_e32 v75, 0, v75, vcc
	s_waitcnt vmcnt(15)
	v_mfma_f32_32x32x16_bf16 v[32:47], v[64:67], v[152:155], v[32:47]
	v_mfma_f32_32x32x16_bf16 v[48:63], v[64:67], v[104:107], v[48:63]
	v_cvt_pk_bf16_f32 v64, v68, v69
	v_cvt_pk_bf16_f32 v65, v70, v71
	v_cvt_pk_bf16_f32 v66, v72, v73
	v_cvt_pk_bf16_f32 v67, v74, v75
	s_waitcnt vmcnt(14)
	s_nop 0
	v_mfma_f32_32x32x16_bf16 v[0:15], v[64:67], v[128:131], v[0:15]
	s_waitcnt vmcnt(13)
	v_mfma_f32_32x32x16_bf16 v[16:31], v[64:67], v[144:147], v[16:31]
	s_waitcnt vmcnt(12)
	v_mfma_f32_32x32x16_bf16 v[32:47], v[64:67], v[136:139], v[32:47]
	v_mfma_f32_32x32x16_bf16 v[48:63], v[64:67], v[104:107], v[48:63]
	s_waitcnt vmcnt(11)
	v_mfma_f32_32x32x16_bf16 v[64:79], v[140:143], v[100:103], 0
	s_and_b64 vcc, s[38:39], s[90:91]
	s_waitcnt vmcnt(10)
	v_mfma_f32_32x32x16_bf16 v[64:79], v[148:151], v[96:99], v[64:79]
	s_waitcnt vmcnt(9)
	v_mfma_f32_32x32x16_bf16 v[64:79], v[156:159], v[92:95], v[64:79]
	s_waitcnt vmcnt(8)
	v_mfma_f32_32x32x16_bf16 v[64:79], v[168:171], v[80:83], v[64:79]
	s_waitcnt vmcnt(7)
	v_mfma_f32_32x32x16_bf16 v[64:79], v[172:175], v[84:87], v[64:79]
	s_waitcnt vmcnt(6)
	v_mfma_f32_32x32x16_bf16 v[64:79], v[184:187], v[88:91], v[64:79]
	s_nop 11
	v_add_f32_e32 v64, v180, v64
	v_add_f32_e32 v65, v180, v65
	v_exp_f32_e32 v64, v64
	v_add_f32_e32 v66, v180, v66
	v_exp_f32_e32 v65, v65
	v_add_f32_e32 v67, v180, v67
	v_exp_f32_e32 v66, v66
	v_add_f32_e32 v68, v180, v68
	v_exp_f32_e32 v67, v67
	v_add_f32_e32 v69, v180, v69
	v_exp_f32_e32 v68, v68
	v_cndmask_b32_e32 v64, 0, v64, vcc
	s_and_b64 vcc, s[40:41], s[90:91]
	v_add_f32_e32 v70, v180, v70
	v_exp_f32_e32 v69, v69
	v_cndmask_b32_e32 v65, 0, v65, vcc
	s_and_b64 vcc, s[42:43], s[90:91]
	v_add_f32_e32 v71, v180, v71
	v_exp_f32_e32 v70, v70
	v_cndmask_b32_e32 v66, 0, v66, vcc
	s_and_b64 vcc, s[44:45], s[90:91]
	v_add_f32_e32 v72, v180, v72
	v_exp_f32_e32 v71, v71
	v_cndmask_b32_e32 v67, 0, v67, vcc
	s_and_b64 vcc, s[46:47], s[90:91]
	v_add_f32_e32 v73, v180, v73
	v_exp_f32_e32 v72, v72
	v_cndmask_b32_e32 v68, 0, v68, vcc
	s_and_b64 vcc, s[48:49], s[90:91]
	v_exp_f32_e32 v73, v73
	v_cndmask_b32_e32 v69, 0, v69, vcc
	s_and_b64 vcc, s[50:51], s[90:91]
	v_add_f32_e32 v74, v180, v74
	v_cndmask_b32_e32 v70, 0, v70, vcc
	s_and_b64 vcc, s[52:53], s[90:91]
	v_add_f32_e32 v75, v180, v75
	v_cndmask_b32_e32 v71, 0, v71, vcc
	v_cvt_pk_bf16_f32 v64, v64, v65
	v_cvt_pk_bf16_f32 v65, v66, v67
	v_cvt_pk_bf16_f32 v66, v68, v69
	v_exp_f32_e32 v68, v74
	s_and_b64 vcc, s[54:55], s[90:91]
	v_add_f32_e32 v76, v180, v76
	v_cvt_pk_bf16_f32 v67, v70, v71
	v_exp_f32_e32 v69, v75
	v_cndmask_b32_e32 v70, 0, v72, vcc
	s_and_b64 vcc, s[56:57], s[90:91]
	v_cndmask_b32_e32 v71, 0, v73, vcc
	v_exp_f32_e32 v72, v76
	v_add_f32_e32 v73, v180, v77
	s_and_b64 vcc, s[58:59], s[90:91]
	v_exp_f32_e32 v73, v73
	v_add_f32_e32 v74, v180, v78
	v_cndmask_b32_e32 v68, 0, v68, vcc
	s_and_b64 vcc, s[60:61], s[90:91]
	v_exp_f32_e32 v74, v74
	v_add_f32_e32 v75, v180, v79
	v_cndmask_b32_e32 v69, 0, v69, vcc
	s_and_b64 vcc, s[62:63], s[90:91]
	v_exp_f32_e32 v75, v75
	v_cndmask_b32_e32 v72, 0, v72, vcc
	s_and_b64 vcc, s[64:65], s[90:91]
	s_waitcnt vmcnt(5)
	v_mfma_f32_32x32x16_bf16 v[0:15], v[64:67], v[132:135], v[0:15]
	v_cndmask_b32_e32 v73, 0, v73, vcc
	s_and_b64 vcc, s[66:67], s[90:91]
	v_cndmask_b32_e32 v74, 0, v74, vcc
	s_and_b64 vcc, s[68:69], s[90:91]
	v_cndmask_b32_e32 v75, 0, v75, vcc
	s_waitcnt vmcnt(4)
	v_mfma_f32_32x32x16_bf16 v[16:31], v[64:67], v[124:127], v[16:31]
	s_waitcnt vmcnt(3)
	v_mfma_f32_32x32x16_bf16 v[32:47], v[64:67], v[120:123], v[32:47]
	v_mfma_f32_32x32x16_bf16 v[48:63], v[64:67], v[104:107], v[48:63]
	v_cvt_pk_bf16_f32 v64, v70, v71
	v_cvt_pk_bf16_f32 v65, v68, v69
	v_cvt_pk_bf16_f32 v66, v72, v73
	v_cvt_pk_bf16_f32 v67, v74, v75
	s_waitcnt vmcnt(2)
	s_nop 0
	v_mfma_f32_32x32x16_bf16 v[0:15], v[64:67], v[108:111], v[0:15]
	s_waitcnt vmcnt(1)
	v_mfma_f32_32x32x16_bf16 v[16:31], v[64:67], v[116:119], v[16:31]
	s_waitcnt vmcnt(0)
	v_mfma_f32_32x32x16_bf16 v[32:47], v[64:67], v[112:115], v[32:47]
	v_mfma_f32_32x32x16_bf16 v[48:63], v[64:67], v[104:107], v[48:63]
	v_mov_b32_e32 v64, v181
	s_nop 5
	v_bfe_u32 v67, v0, 16, 1
	v_ashrrev_i32_e32 v66, 3, v64
	v_and_b32_e32 v68, 31, v64
	v_and_b32_e32 v65, -4, v66
	s_movk_i32 s3, 0xc0
	v_add3_u32 v69, v0, v67, s2
	v_mul_lo_u32 v67, v65, s3
	v_lshlrev_b32_e32 v0, 1, v68
	v_cmp_eq_u32_e32 vcc, 0, v68
	v_add3_u32 v68, s77, v67, v0
	ds_write_b16_d16_hi v68, v69
	v_bfe_u32 v69, v16, 16, 1
	v_add3_u32 v16, v16, v69, s2
	ds_write_b16_d16_hi v68, v16 offset:64
	v_bfe_u32 v16, v32, 16, 1
	v_add3_u32 v16, v32, v16, s2
	ds_write_b16_d16_hi v68, v16 offset:128
	s_and_saveexec_b64 s[72:73], vcc
	v_lshl_add_u32 v16, v65, 2, s77
	ds_write_b32 v16, v48 offset:6144
	s_or_b64 exec, exec, s[72:73]
	v_bfe_u32 v16, v1, 16, 1
	v_add3_u32 v16, v1, v16, s2
	v_add_u32_e32 v1, 0xc0, v67
	v_add3_u32 v32, s77, v1, v0
	ds_write_b16_d16_hi v32, v16
	v_bfe_u32 v16, v17, 16, 1
	v_add3_u32 v16, v17, v16, s2
	ds_write_b16_d16_hi v32, v16 offset:64
	v_bfe_u32 v16, v33, 16, 1
	v_add3_u32 v16, v33, v16, s2
	ds_write_b16_d16_hi v32, v16 offset:128
	s_and_saveexec_b64 s[72:73], vcc
	v_lshl_add_u32 v16, v65, 2, s77
	ds_write_b32 v16, v49 offset:6148
	s_or_b64 exec, exec, s[72:73]
	v_bfe_u32 v16, v2, 16, 1
	v_add_u32_e32 v1, 0xc0, v1
	v_add3_u32 v2, v2, v16, s2
	v_add3_u32 v16, s77, v1, v0
	ds_write_b16_d16_hi v16, v2
	v_bfe_u32 v2, v18, 16, 1
	v_add3_u32 v2, v18, v2, s2
	ds_write_b16_d16_hi v16, v2 offset:64
	v_bfe_u32 v2, v34, 16, 1
	v_add3_u32 v2, v34, v2, s2
	ds_write_b16_d16_hi v16, v2 offset:128
	s_and_saveexec_b64 s[72:73], vcc
	s_movk_i32 s88, 0x80
	s_mov_b32 s89, s6
	s_mov_b32 s90, s7
	s_mov_b32 s91, s8
	v_lshl_add_u32 v2, v65, 2, s77
	ds_write_b32 v2, v50 offset:6152
	s_or_b64 exec, exec, s[72:73]
	v_or_b32_e32 v2, 3, v66
	v_bfe_u32 v16, v3, 16, 1
	v_add3_u32 v3, v3, v16, s2
	v_mul_lo_u32 v16, v2, s3
	v_add3_u32 v16, s77, v16, v0
	ds_write_b16_d16_hi v16, v3
	v_bfe_u32 v3, v19, 16, 1
	v_add3_u32 v3, v19, v3, s2
	ds_write_b16_d16_hi v16, v3 offset:64
	v_bfe_u32 v3, v35, 16, 1
	v_add3_u32 v3, v35, v3, s2
	ds_write_b16_d16_hi v16, v3 offset:128
	s_and_saveexec_b64 s[72:73], vcc
	v_lshl_add_u32 v2, v2, 2, s77
	ds_write_b32 v2, v51 offset:6144
	s_or_b64 exec, exec, s[72:73]
	v_bfe_u32 v2, v4, 16, 1
	v_add_u32_e32 v1, 0x480, v1
	v_add3_u32 v2, v4, v2, s2
	v_add3_u32 v3, s77, v1, v0
	ds_write_b16_d16_hi v3, v2
	v_bfe_u32 v2, v20, 16, 1
	v_add3_u32 v2, v20, v2, s2
	ds_write_b16_d16_hi v3, v2 offset:64
	v_bfe_u32 v2, v36, 16, 1
	v_add3_u32 v2, v36, v2, s2
	ds_write_b16_d16_hi v3, v2 offset:128
	s_and_saveexec_b64 s[72:73], vcc
	v_lshl_add_u32 v2, v65, 2, s77
	ds_write_b32 v2, v52 offset:6176
	s_or_b64 exec, exec, s[72:73]
	v_bfe_u32 v2, v5, 16, 1
	v_add_u32_e32 v1, 0xc0, v1
	v_add3_u32 v2, v5, v2, s2
	v_add3_u32 v3, s77, v1, v0
	ds_write_b16_d16_hi v3, v2
	v_bfe_u32 v2, v21, 16, 1
	v_add3_u32 v2, v21, v2, s2
	ds_write_b16_d16_hi v3, v2 offset:64
	v_bfe_u32 v2, v37, 16, 1
	v_add3_u32 v2, v37, v2, s2
	ds_write_b16_d16_hi v3, v2 offset:128
	s_and_saveexec_b64 s[72:73], vcc
	v_lshl_add_u32 v2, v65, 2, s77
	ds_write_b32 v2, v53 offset:6180
	s_or_b64 exec, exec, s[72:73]
	v_bfe_u32 v2, v6, 16, 1
	v_add_u32_e32 v1, 0xc0, v1
	v_add3_u32 v2, v6, v2, s2
	v_add3_u32 v3, s77, v1, v0
	ds_write_b16_d16_hi v3, v2
	v_bfe_u32 v2, v22, 16, 1
	v_add3_u32 v2, v22, v2, s2
	ds_write_b16_d16_hi v3, v2 offset:64
	v_bfe_u32 v2, v38, 16, 1
	v_add3_u32 v2, v38, v2, s2
	ds_write_b16_d16_hi v3, v2 offset:128
	s_and_saveexec_b64 s[72:73], vcc
	v_lshl_add_u32 v2, v65, 2, s77
	ds_write_b32 v2, v54 offset:6184
	s_or_b64 exec, exec, s[72:73]
	v_bfe_u32 v2, v7, 16, 1
	v_add_u32_e32 v1, 0xc0, v1
	v_add3_u32 v2, v7, v2, s2
	v_add3_u32 v3, s77, v1, v0
	ds_write_b16_d16_hi v3, v2
	v_bfe_u32 v2, v23, 16, 1
	v_add3_u32 v2, v23, v2, s2
	ds_write_b16_d16_hi v3, v2 offset:64
	v_bfe_u32 v2, v39, 16, 1
	v_add3_u32 v2, v39, v2, s2
	ds_write_b16_d16_hi v3, v2 offset:128
	s_and_saveexec_b64 s[72:73], vcc
	v_lshl_add_u32 v2, v65, 2, s77
	ds_write_b32 v2, v55 offset:6188
	s_or_b64 exec, exec, s[72:73]
	v_bfe_u32 v2, v8, 16, 1
	v_add_u32_e32 v1, 0x3c0, v1
	v_add3_u32 v2, v8, v2, s2
	v_add3_u32 v3, s77, v1, v0
	ds_write_b16_d16_hi v3, v2
	v_bfe_u32 v2, v24, 16, 1
	v_add3_u32 v2, v24, v2, s2
	ds_write_b16_d16_hi v3, v2 offset:64
	v_bfe_u32 v2, v40, 16, 1
	v_add3_u32 v2, v40, v2, s2
	ds_write_b16_d16_hi v3, v2 offset:128
	s_and_saveexec_b64 s[72:73], vcc
	v_lshl_add_u32 v2, v65, 2, s77
	ds_write_b32 v2, v56 offset:6208
	s_or_b64 exec, exec, s[72:73]
	v_bfe_u32 v2, v9, 16, 1
	v_add_u32_e32 v1, 0xc0, v1
	v_add3_u32 v2, v9, v2, s2
	v_add3_u32 v3, s77, v1, v0
	ds_write_b16_d16_hi v3, v2
	v_bfe_u32 v2, v25, 16, 1
	v_add3_u32 v2, v25, v2, s2
	ds_write_b16_d16_hi v3, v2 offset:64
	v_bfe_u32 v2, v41, 16, 1
	v_add3_u32 v2, v41, v2, s2
	ds_write_b16_d16_hi v3, v2 offset:128
	s_and_saveexec_b64 s[72:73], vcc
	v_lshl_add_u32 v2, v65, 2, s77
	ds_write_b32 v2, v57 offset:6212
	s_or_b64 exec, exec, s[72:73]
	v_bfe_u32 v2, v10, 16, 1
	v_add_u32_e32 v1, 0xc0, v1
	v_add3_u32 v2, v10, v2, s2
	v_add3_u32 v3, s77, v1, v0
	ds_write_b16_d16_hi v3, v2
	v_bfe_u32 v2, v26, 16, 1
	v_add3_u32 v2, v26, v2, s2
	ds_write_b16_d16_hi v3, v2 offset:64
	v_bfe_u32 v2, v42, 16, 1
	v_add3_u32 v2, v42, v2, s2
	ds_write_b16_d16_hi v3, v2 offset:128
	s_and_saveexec_b64 s[72:73], vcc
	v_lshl_add_u32 v2, v65, 2, s77
	ds_write_b32 v2, v58 offset:6216
	s_or_b64 exec, exec, s[72:73]
	v_bfe_u32 v2, v11, 16, 1
	v_add_u32_e32 v1, 0xc0, v1
	v_add3_u32 v2, v11, v2, s2
	v_add3_u32 v3, s77, v1, v0
	ds_write_b16_d16_hi v3, v2
	v_bfe_u32 v2, v27, 16, 1
	v_add3_u32 v2, v27, v2, s2
	ds_write_b16_d16_hi v3, v2 offset:64
	v_bfe_u32 v2, v43, 16, 1
	v_add3_u32 v2, v43, v2, s2
	ds_write_b16_d16_hi v3, v2 offset:128
	s_and_saveexec_b64 s[72:73], vcc
	v_lshl_add_u32 v2, v65, 2, s77
	ds_write_b32 v2, v59 offset:6220
	s_or_b64 exec, exec, s[72:73]
	v_bfe_u32 v2, v12, 16, 1
	v_add_u32_e32 v1, 0x3c0, v1
	v_add3_u32 v2, v12, v2, s2
	v_add3_u32 v3, s77, v1, v0
	ds_write_b16_d16_hi v3, v2
	v_bfe_u32 v2, v28, 16, 1
	v_add3_u32 v2, v28, v2, s2
	ds_write_b16_d16_hi v3, v2 offset:64
	v_bfe_u32 v2, v44, 16, 1
	v_add3_u32 v2, v44, v2, s2
	ds_write_b16_d16_hi v3, v2 offset:128
	s_and_saveexec_b64 s[72:73], vcc
	v_lshl_add_u32 v2, v65, 2, s77
	ds_write_b32 v2, v60 offset:6240
	s_or_b64 exec, exec, s[72:73]
	v_bfe_u32 v2, v13, 16, 1
	v_add_u32_e32 v1, 0xc0, v1
	v_add3_u32 v2, v13, v2, s2
	v_add3_u32 v3, s77, v1, v0
	ds_write_b16_d16_hi v3, v2
	v_bfe_u32 v2, v29, 16, 1
	v_add3_u32 v2, v29, v2, s2
	ds_write_b16_d16_hi v3, v2 offset:64
	v_bfe_u32 v2, v45, 16, 1
	v_add3_u32 v2, v45, v2, s2
	ds_write_b16_d16_hi v3, v2 offset:128
	s_and_saveexec_b64 s[72:73], vcc
	v_lshl_add_u32 v2, v65, 2, s77
	ds_write_b32 v2, v61 offset:6244
	s_or_b64 exec, exec, s[72:73]
	v_add_u32_e32 v1, 0xc0, v1
	v_add3_u32 v0, s77, v1, v0
	v_bfe_u32 v1, v30, 16, 1
	v_add3_u32 v1, v30, v1, s2
	v_bfe_u32 v2, v14, 16, 1
	ds_write_b16_d16_hi v0, v1 offset:64
	v_bfe_u32 v1, v46, 16, 1
	v_add3_u32 v2, v14, v2, s2
	v_add3_u32 v1, v46, v1, s2
	ds_write_b16_d16_hi v0, v2
	ds_write_b16_d16_hi v0, v1 offset:128
	s_and_saveexec_b64 s[72:73], vcc
	v_lshl_add_u32 v1, v65, 2, s77
	ds_write_b32 v1, v62 offset:6248
	s_or_b64 exec, exec, s[72:73]
	v_bfe_u32 v1, v15, 16, 1
	v_add3_u32 v1, v15, v1, s2
	ds_write_b16_d16_hi v0, v1 offset:192
	v_bfe_u32 v1, v31, 16, 1
	v_add3_u32 v1, v31, v1, s2
	ds_write_b16_d16_hi v0, v1 offset:256
	v_bfe_u32 v1, v47, 16, 1
	v_add3_u32 v1, v47, v1, s2
	ds_write_b16_d16_hi v0, v1 offset:320
	s_and_saveexec_b64 s[72:73], vcc
	v_lshl_add_u32 v0, v65, 2, s77
	ds_write_b32 v0, v63 offset:6252
	s_or_b64 exec, exec, s[72:73]
	s_mov_b32 s4, 0x2aaaaaab
	v_mul_hi_i32 v0, v64, s4
	v_lshrrev_b32_e32 v1, 31, v0
	v_ashrrev_i32_e32 v0, 1, v0
	v_add_u32_e32 v0, v0, v1
	s_waitcnt lgkmcnt(0)
	v_mul_lo_u32 v1, v0, 12
	v_sub_u32_e32 v10, v64, v1
	v_lshl_add_u32 v1, v64, 4, s77
	v_add_u32_e32 v0, s82, v0
	ds_read_b128 v[2:5], v1
	v_ashrrev_i32_e32 v1, 31, v0
	v_lshlrev_b64 v[0:1], s33, v[0:1]
	v_lshl_add_u64 v[6:7], v[0:1], 0, s[94:95]
	v_mov_b64_e32 v[0:1], s[84:85]
	v_mad_u64_u32 v[8:9], s[70:71], v6, s81, v[0:1]
	v_mov_b32_e32 v6, v9
	v_mad_u64_u32 v[6:7], s[70:71], v7, s81, v[6:7]
	v_mov_b32_e32 v9, v6
	v_lshl_add_u64 v[6:7], v[8:9], 0, s[92:93]
	v_lshlrev_b32_e32 v8, 3, v10
	v_ashrrev_i32_e32 v9, 31, v8
	v_lshl_add_u64 v[6:7], v[8:9], 1, v[6:7]
	s_movk_i32 s3, 0x1000
	v_add_co_u32_e32 v6, vcc, s3, v6
	s_nop 1
	v_addc_co_u32_e32 v7, vcc, 0, v7, vcc
	s_waitcnt lgkmcnt(0)
	global_store_dwordx4 v[6:7], v[2:5], off offset:512
	s_nop 1
	v_add_u32_e32 v2, 64, v64
	v_mul_hi_i32 v3, v2, s4
	v_lshrrev_b32_e32 v4, 31, v3
	v_ashrrev_i32_e32 v3, 1, v3
	v_add_u32_e32 v6, v3, v4
	v_mul_lo_u32 v3, v6, 12
	v_add_u32_e32 v6, s82, v6
	v_ashrrev_i32_e32 v7, 31, v6
	v_lshlrev_b64 v[6:7], s33, v[6:7]
	v_lshl_add_u64 v[6:7], v[6:7], 0, s[94:95]
	v_mad_u64_u32 v[8:9], s[70:71], v6, s81, v[0:1]
	v_mov_b32_e32 v6, v9
	v_mad_u64_u32 v[6:7], s[70:71], v7, s81, v[6:7]
	v_sub_u32_e32 v10, v2, v3
	v_lshl_add_u32 v2, v2, 4, s77
	v_mov_b32_e32 v9, v6
	ds_read_b128 v[2:5], v2
	v_lshl_add_u64 v[6:7], v[8:9], 0, s[92:93]
	v_lshlrev_b32_e32 v8, 3, v10
	v_ashrrev_i32_e32 v9, 31, v8
	v_lshl_add_u64 v[6:7], v[8:9], 1, v[6:7]
	v_add_co_u32_e32 v6, vcc, s3, v6
	s_nop 1
	v_addc_co_u32_e32 v7, vcc, 0, v7, vcc
	s_waitcnt lgkmcnt(0)
	global_store_dwordx4 v[6:7], v[2:5], off offset:512
	s_nop 1
	v_add_u32_e32 v2, 0x80, v64
	v_mul_hi_i32 v3, v2, s4
	v_lshrrev_b32_e32 v4, 31, v3
	v_ashrrev_i32_e32 v3, 1, v3
	v_add_u32_e32 v6, v3, v4
	v_mul_lo_u32 v3, v6, 12
	v_add_u32_e32 v6, s82, v6
	v_ashrrev_i32_e32 v7, 31, v6
	v_lshlrev_b64 v[6:7], s33, v[6:7]
	v_lshl_add_u64 v[6:7], v[6:7], 0, s[94:95]
	v_mad_u64_u32 v[8:9], s[70:71], v6, s81, v[0:1]
	v_mov_b32_e32 v6, v9
	v_mad_u64_u32 v[6:7], s[70:71], v7, s81, v[6:7]
	v_sub_u32_e32 v10, v2, v3
	v_lshl_add_u32 v2, v2, 4, s77
	v_mov_b32_e32 v9, v6
	ds_read_b128 v[2:5], v2
	v_lshl_add_u64 v[6:7], v[8:9], 0, s[92:93]
	v_lshlrev_b32_e32 v8, 3, v10
	v_ashrrev_i32_e32 v9, 31, v8
	v_lshl_add_u64 v[6:7], v[8:9], 1, v[6:7]
	v_add_co_u32_e32 v6, vcc, s3, v6
	s_nop 1
	v_addc_co_u32_e32 v7, vcc, 0, v7, vcc
	s_waitcnt lgkmcnt(0)
	global_store_dwordx4 v[6:7], v[2:5], off offset:512
	s_nop 1
	v_add_u32_e32 v2, 0xc0, v64
	v_mul_hi_i32 v3, v2, s4
	v_lshrrev_b32_e32 v4, 31, v3
	v_ashrrev_i32_e32 v3, 1, v3
	v_add_u32_e32 v6, v3, v4
	v_mul_lo_u32 v3, v6, 12
	v_add_u32_e32 v6, s82, v6
	v_ashrrev_i32_e32 v7, 31, v6
	v_lshlrev_b64 v[6:7], s33, v[6:7]
	v_lshl_add_u64 v[6:7], v[6:7], 0, s[94:95]
	v_mad_u64_u32 v[8:9], s[70:71], v6, s81, v[0:1]
	v_mov_b32_e32 v6, v9
	v_mad_u64_u32 v[6:7], s[70:71], v7, s81, v[6:7]
	v_sub_u32_e32 v10, v2, v3
	v_lshl_add_u32 v2, v2, 4, s77
	v_mov_b32_e32 v9, v6
	ds_read_b128 v[2:5], v2
	v_lshl_add_u64 v[6:7], v[8:9], 0, s[92:93]
	v_lshlrev_b32_e32 v8, 3, v10
	v_ashrrev_i32_e32 v9, 31, v8
	v_lshl_add_u64 v[6:7], v[8:9], 1, v[6:7]
	v_add_co_u32_e32 v6, vcc, s3, v6
	s_nop 1
	v_addc_co_u32_e32 v7, vcc, 0, v7, vcc
	s_waitcnt lgkmcnt(0)
	global_store_dwordx4 v[6:7], v[2:5], off offset:512
	s_nop 1
	v_add_u32_e32 v2, 0x100, v64
	v_mul_hi_i32 v3, v2, s4
	v_lshrrev_b32_e32 v4, 31, v3
	v_ashrrev_i32_e32 v3, 1, v3
	v_add_u32_e32 v6, v3, v4
	v_mul_lo_u32 v3, v6, 12
	v_add_u32_e32 v6, s82, v6
	v_ashrrev_i32_e32 v7, 31, v6
	v_lshlrev_b64 v[6:7], s33, v[6:7]
	v_lshl_add_u64 v[6:7], v[6:7], 0, s[94:95]
	v_mad_u64_u32 v[8:9], s[70:71], v6, s81, v[0:1]
	v_mov_b32_e32 v6, v9
	v_mad_u64_u32 v[6:7], s[70:71], v7, s81, v[6:7]
	v_sub_u32_e32 v10, v2, v3
	v_lshl_add_u32 v2, v2, 4, s77
	v_mov_b32_e32 v9, v6
	ds_read_b128 v[2:5], v2
	v_lshl_add_u64 v[6:7], v[8:9], 0, s[92:93]
	v_lshlrev_b32_e32 v8, 3, v10
	v_ashrrev_i32_e32 v9, 31, v8
	v_lshl_add_u64 v[6:7], v[8:9], 1, v[6:7]
	v_add_co_u32_e32 v6, vcc, s3, v6
	s_nop 1
	v_addc_co_u32_e32 v7, vcc, 0, v7, vcc
	s_waitcnt lgkmcnt(0)
	global_store_dwordx4 v[6:7], v[2:5], off offset:512
	s_nop 1
	v_add_u32_e32 v2, 0x140, v64
	v_mul_hi_i32 v3, v2, s4
	v_lshrrev_b32_e32 v4, 31, v3
	v_ashrrev_i32_e32 v3, 1, v3
	v_add_u32_e32 v6, v3, v4
	v_mul_lo_u32 v3, v6, 12
	v_add_u32_e32 v6, s82, v6
	v_ashrrev_i32_e32 v7, 31, v6
	v_lshlrev_b64 v[6:7], s33, v[6:7]
	v_lshl_add_u64 v[6:7], v[6:7], 0, s[94:95]
	v_mad_u64_u32 v[0:1], s[70:71], v6, s81, v[0:1]
	v_mov_b32_e32 v6, v1
	v_sub_u32_e32 v8, v2, v3
	v_mad_u64_u32 v[6:7], s[70:71], v7, s81, v[6:7]
	v_lshl_add_u32 v2, v2, 4, s77
	v_mov_b32_e32 v1, v6
	v_lshlrev_b32_e32 v6, 3, v8
	ds_read_b128 v[2:5], v2
	v_lshl_add_u64 v[0:1], v[0:1], 0, s[92:93]
	v_ashrrev_i32_e32 v7, 31, v6
	v_lshl_add_u64 v[0:1], v[6:7], 1, v[0:1]
	v_add_co_u32_e32 v0, vcc, 0x1000, v0
	s_nop 1
	v_addc_co_u32_e32 v1, vcc, 0, v1, vcc
	v_cmp_gt_i32_e32 vcc, 32, v64
	s_waitcnt lgkmcnt(0)
	global_store_dwordx4 v[0:1], v[2:5], off offset:512
	s_and_saveexec_b64 s[72:73], vcc
	s_cbranch_execz .LBB0_527
	v_add_u32_e32 v0, s82, v64
	v_ashrrev_i32_e32 v1, 31, v0
	v_lshlrev_b64 v[0:1], s33, v[0:1]
	v_readlane_b32 s4, v254, 55
	v_lshl_add_u64 v[0:1], v[0:1], 0, s[94:95]
	v_lshl_add_u32 v2, v64, 2, s77
	v_readlane_b32 s5, v254, 56
	ds_read_b32 v4, v2 offset:6144
	s_nop 0
	v_mad_u64_u32 v[2:3], s[70:71], v0, 48, s[4:5]
	v_mov_b32_e32 v0, v3
	v_mad_u64_u32 v[0:1], s[70:71], v1, 48, v[0:1]
	v_mov_b32_e32 v3, v0
	v_lshl_add_u64 v[0:1], s[96:97], 2, v[2:3]
	s_waitcnt lgkmcnt(0)
	global_store_dword v[0:1], v4, off
	s_branch .LBB0_527
